# speedup vs baseline: 1.0038x; 1.0038x over previous
; DEVI void rwkv_scan_item(const Params& p, const int item, char* smem) {
;     ...
;       const float* sb = buf + (c & 1) * 12288 + kp * 4;
;       float* yb = ybuf + (c & 1) * 2048 + row16 * 4 + (kp >> 2);
;       const int vofs = 320 + rq * 16 + row16 - kp * 4;
.LBB0_514:
	s_and_saveexec_b64 s[64:65], s[2:3]
	s_xor_b64 s[64:65], exec, s[64:65]
	s_cbranch_execz .LBB0_519
	s_and_b32 s58, s78, 1
	s_mul_i32 s58, s58, 0xc000
	v_add_u32_e32 v98, s58, v81
	ds_read_b128 v[2:5], v98
	v_lshl_add_u32 v99, v63, 2, v98
	ds_read_b32 v22, v99 offset:1280
	ds_read_b128 v[14:17], v98 offset:768
	ds_read_b128 v[6:9], v98 offset:256
	ds_read_b128 v[10:13], v98 offset:512
	ds_read_b128 v[18:21], v98 offset:1024
	s_and_b32 s58, s78, 1
	s_lshl_b32 s58, s58, 14
	s_add_i32 s58, s58, 0x18010
	v_bfe_u32 v41, v0, 4, 4
	v_bfe_u32 v80, v0, 1, 3
	v_lshlrev_b32_e32 v41, 5, v41
	v_lshl_add_u32 v41, v80, 2, v41
	v_add_u32_e32 v97, s58, v41
	s_waitcnt lgkmcnt(0)
	v_pk_mul_f32 v[104:105], v[100:101], v[2:3]
	s_nop 0
	v_pk_fma_f32 v[104:105], v[102:103], v[4:5], v[104:105]
	s_nop 0
	v_add_f32_e32 v104, v104, v105
	ds_read_b32 v40, v99 offset:2816
	ds_read_b128 v[36:39], v98 offset:2304
	v_add_f32_dpp v104, v104, v104 quad_perm:[1,0,3,2] row_mask:0xf bank_mask:0xf bound_ctrl:1
	ds_read_b128 v[24:27], v98 offset:1536
	ds_read_b128 v[28:31], v98 offset:1792
	v_add_f32_dpp v104, v104, v104 quad_perm:[2,3,0,1] row_mask:0xf bank_mask:0xf bound_ctrl:1
	v_pk_mul_f32 v[14:15], v[14:15], v[22:23] op_sel_hi:[1,0]
	v_pk_mul_f32 v[16:17], v[16:17], v[22:23] op_sel_hi:[1,0]
	v_add_f32_dpp v104, v104, v104 row_half_mirror row_mask:0xf bank_mask:0xf bound_ctrl:1
	s_waitcnt lgkmcnt(5)
	v_pk_fma_f32 v[14:15], v[100:101], v[6:7], v[14:15]
	v_pk_fma_f32 v[16:17], v[102:103], v[8:9], v[16:17]
	v_add_f32_dpp v104, v104, v104 row_mirror row_mask:0xf bank_mask:0xf bound_ctrl:1
	v_pk_fma_f32 v[100:101], v[10:11], v[104:105], v[14:15] op_sel_hi:[1,0,1] neg_lo:[0,1,0] neg_hi:[0,1,0]
	v_pk_fma_f32 v[102:103], v[12:13], v[104:105], v[16:17] op_sel_hi:[1,0,1] neg_lo:[0,1,0] neg_hi:[0,1,0]
	v_pk_mul_f32 v[106:107], v[100:101], v[18:19]
	ds_read_b128 v[32:35], v98 offset:2048
	v_pk_fma_f32 v[106:107], v[102:103], v[20:21], v[106:107]
	s_waitcnt lgkmcnt(2)
	v_pk_mul_f32 v[104:105], v[100:101], v[24:25]
	v_add_f32_e32 v106, v106, v107
	ds_read_b128 v[84:87], v98 offset:2560
	v_pk_fma_f32 v[104:105], v[102:103], v[26:27], v[104:105]
	v_add_f32_dpp v106, v106, v106 quad_perm:[1,0,3,2] row_mask:0xf bank_mask:0xf bound_ctrl:1
	v_add_f32_e32 v104, v104, v105
	ds_write_b32 v97, v106 offset:0
	ds_read_b32 v22, v99 offset:4352
	ds_read_b128 v[14:17], v98 offset:3840
	v_add_f32_dpp v104, v104, v104 quad_perm:[1,0,3,2] row_mask:0xf bank_mask:0xf bound_ctrl:1
	ds_read_b128 v[2:5], v98 offset:3072
	ds_read_b128 v[6:9], v98 offset:3328
	v_add_f32_dpp v104, v104, v104 quad_perm:[2,3,0,1] row_mask:0xf bank_mask:0xf bound_ctrl:1
	v_pk_mul_f32 v[36:37], v[36:37], v[40:41] op_sel_hi:[1,0]
	v_pk_mul_f32 v[38:39], v[38:39], v[40:41] op_sel_hi:[1,0]
	v_add_f32_dpp v104, v104, v104 row_half_mirror row_mask:0xf bank_mask:0xf bound_ctrl:1
	s_waitcnt lgkmcnt(5)
	v_pk_fma_f32 v[36:37], v[100:101], v[28:29], v[36:37]
	v_pk_fma_f32 v[38:39], v[102:103], v[30:31], v[38:39]
	v_add_f32_dpp v104, v104, v104 row_mirror row_mask:0xf bank_mask:0xf bound_ctrl:1
	v_pk_fma_f32 v[100:101], v[32:33], v[104:105], v[36:37] op_sel_hi:[1,0,1] neg_lo:[0,1,0] neg_hi:[0,1,0]
	v_pk_fma_f32 v[102:103], v[34:35], v[104:105], v[38:39] op_sel_hi:[1,0,1] neg_lo:[0,1,0] neg_hi:[0,1,0]
	v_pk_mul_f32 v[106:107], v[100:101], v[84:85]
	ds_read_b128 v[10:13], v98 offset:3584
	v_pk_fma_f32 v[106:107], v[102:103], v[86:87], v[106:107]
	s_waitcnt lgkmcnt(2)
	v_pk_mul_f32 v[104:105], v[100:101], v[2:3]
	v_add_f32_e32 v106, v106, v107
	ds_read_b128 v[18:21], v98 offset:4096
	v_pk_fma_f32 v[104:105], v[102:103], v[4:5], v[104:105]
	v_add_f32_dpp v106, v106, v106 quad_perm:[1,0,3,2] row_mask:0xf bank_mask:0xf bound_ctrl:1
	v_add_f32_e32 v104, v104, v105
	ds_write_b32 v97, v106 offset:512
	ds_read_b32 v40, v99 offset:5888
	ds_read_b128 v[36:39], v98 offset:5376
	v_add_f32_dpp v104, v104, v104 quad_perm:[1,0,3,2] row_mask:0xf bank_mask:0xf bound_ctrl:1
	ds_read_b128 v[24:27], v98 offset:4608
	ds_read_b128 v[28:31], v98 offset:4864
	v_add_f32_dpp v104, v104, v104 quad_perm:[2,3,0,1] row_mask:0xf bank_mask:0xf bound_ctrl:1
	v_pk_mul_f32 v[14:15], v[14:15], v[22:23] op_sel_hi:[1,0]
	v_pk_mul_f32 v[16:17], v[16:17], v[22:23] op_sel_hi:[1,0]
	v_add_f32_dpp v104, v104, v104 row_half_mirror row_mask:0xf bank_mask:0xf bound_ctrl:1
	s_waitcnt lgkmcnt(5)
	v_pk_fma_f32 v[14:15], v[100:101], v[6:7], v[14:15]
	v_pk_fma_f32 v[16:17], v[102:103], v[8:9], v[16:17]
	v_add_f32_dpp v104, v104, v104 row_mirror row_mask:0xf bank_mask:0xf bound_ctrl:1
	v_pk_fma_f32 v[100:101], v[10:11], v[104:105], v[14:15] op_sel_hi:[1,0,1] neg_lo:[0,1,0] neg_hi:[0,1,0]
	v_pk_fma_f32 v[102:103], v[12:13], v[104:105], v[16:17] op_sel_hi:[1,0,1] neg_lo:[0,1,0] neg_hi:[0,1,0]
	v_pk_mul_f32 v[106:107], v[100:101], v[18:19]
	ds_read_b128 v[32:35], v98 offset:5120
	v_pk_fma_f32 v[106:107], v[102:103], v[20:21], v[106:107]
	s_waitcnt lgkmcnt(2)
	v_pk_mul_f32 v[104:105], v[100:101], v[24:25]
	v_add_f32_e32 v106, v106, v107
	ds_read_b128 v[84:87], v98 offset:5632
	v_pk_fma_f32 v[104:105], v[102:103], v[26:27], v[104:105]
	v_add_f32_dpp v106, v106, v106 quad_perm:[1,0,3,2] row_mask:0xf bank_mask:0xf bound_ctrl:1
	v_add_f32_e32 v104, v104, v105
	ds_write_b32 v97, v106 offset:1024
	ds_read_b32 v22, v99 offset:7424
	ds_read_b128 v[14:17], v98 offset:6912
	v_add_f32_dpp v104, v104, v104 quad_perm:[1,0,3,2] row_mask:0xf bank_mask:0xf bound_ctrl:1
	ds_read_b128 v[2:5], v98 offset:6144
	ds_read_b128 v[6:9], v98 offset:6400
	v_add_f32_dpp v104, v104, v104 quad_perm:[2,3,0,1] row_mask:0xf bank_mask:0xf bound_ctrl:1
	v_pk_mul_f32 v[36:37], v[36:37], v[40:41] op_sel_hi:[1,0]
	v_pk_mul_f32 v[38:39], v[38:39], v[40:41] op_sel_hi:[1,0]
	v_add_f32_dpp v104, v104, v104 row_half_mirror row_mask:0xf bank_mask:0xf bound_ctrl:1
	s_waitcnt lgkmcnt(5)
; DEVI void rwkv_scan_item(const Params& p, const int item, char* smem) {
;     ...
; #pragma unroll 2
;       for (int s = 0; s < 32; s += 2) {
;         RW_LD(s + 1, B)
;         __builtin_amdgcn_sched_barrier(0);
;         RW_STEP(s, A)
;         __builtin_amdgcn_sched_barrier(0);
;         if (s + 2 < 32) RW_LD(s + 2, A)
;         __builtin_amdgcn_sched_barrier(0);
;         RW_STEP(s + 1, B)
;         __builtin_amdgcn_sched_barrier(0);
;       }
	v_pk_fma_f32 v[36:37], v[100:101], v[28:29], v[36:37]
	v_pk_fma_f32 v[38:39], v[102:103], v[30:31], v[38:39]
	v_add_f32_dpp v104, v104, v104 row_mirror row_mask:0xf bank_mask:0xf bound_ctrl:1
	v_pk_fma_f32 v[100:101], v[32:33], v[104:105], v[36:37] op_sel_hi:[1,0,1] neg_lo:[0,1,0] neg_hi:[0,1,0]
	v_pk_fma_f32 v[102:103], v[34:35], v[104:105], v[38:39] op_sel_hi:[1,0,1] neg_lo:[0,1,0] neg_hi:[0,1,0]
	v_pk_mul_f32 v[106:107], v[100:101], v[84:85]
	ds_read_b128 v[10:13], v98 offset:6656
	v_pk_fma_f32 v[106:107], v[102:103], v[86:87], v[106:107]
	s_waitcnt lgkmcnt(2)
	v_pk_mul_f32 v[104:105], v[100:101], v[2:3]
	v_add_f32_e32 v106, v106, v107
	ds_read_b128 v[18:21], v98 offset:7168
	v_pk_fma_f32 v[104:105], v[102:103], v[4:5], v[104:105]
	v_add_f32_dpp v106, v106, v106 quad_perm:[1,0,3,2] row_mask:0xf bank_mask:0xf bound_ctrl:1
	v_add_f32_e32 v104, v104, v105
	ds_write_b32 v97, v106 offset:1536
	ds_read_b32 v40, v99 offset:8960
	ds_read_b128 v[36:39], v98 offset:8448
	v_add_f32_dpp v104, v104, v104 quad_perm:[1,0,3,2] row_mask:0xf bank_mask:0xf bound_ctrl:1
	ds_read_b128 v[24:27], v98 offset:7680
	ds_read_b128 v[28:31], v98 offset:7936
	v_add_f32_dpp v104, v104, v104 quad_perm:[2,3,0,1] row_mask:0xf bank_mask:0xf bound_ctrl:1
	v_pk_mul_f32 v[14:15], v[14:15], v[22:23] op_sel_hi:[1,0]
	v_pk_mul_f32 v[16:17], v[16:17], v[22:23] op_sel_hi:[1,0]
	v_add_f32_dpp v104, v104, v104 row_half_mirror row_mask:0xf bank_mask:0xf bound_ctrl:1
	s_waitcnt lgkmcnt(5)
	v_pk_fma_f32 v[14:15], v[100:101], v[6:7], v[14:15]
	v_pk_fma_f32 v[16:17], v[102:103], v[8:9], v[16:17]
	v_add_f32_dpp v104, v104, v104 row_mirror row_mask:0xf bank_mask:0xf bound_ctrl:1
	v_pk_fma_f32 v[100:101], v[10:11], v[104:105], v[14:15] op_sel_hi:[1,0,1] neg_lo:[0,1,0] neg_hi:[0,1,0]
	v_pk_fma_f32 v[102:103], v[12:13], v[104:105], v[16:17] op_sel_hi:[1,0,1] neg_lo:[0,1,0] neg_hi:[0,1,0]
	v_pk_mul_f32 v[106:107], v[100:101], v[18:19]
	ds_read_b128 v[32:35], v98 offset:8192
	v_pk_fma_f32 v[106:107], v[102:103], v[20:21], v[106:107]
	s_waitcnt lgkmcnt(2)
	v_pk_mul_f32 v[104:105], v[100:101], v[24:25]
	v_add_f32_e32 v106, v106, v107
	ds_read_b128 v[84:87], v98 offset:8704
	v_pk_fma_f32 v[104:105], v[102:103], v[26:27], v[104:105]
	v_add_f32_dpp v106, v106, v106 quad_perm:[1,0,3,2] row_mask:0xf bank_mask:0xf bound_ctrl:1
	v_add_f32_e32 v104, v104, v105
	ds_write_b32 v97, v106 offset:2048
	ds_read_b32 v22, v99 offset:10496
	ds_read_b128 v[14:17], v98 offset:9984
	v_add_f32_dpp v104, v104, v104 quad_perm:[1,0,3,2] row_mask:0xf bank_mask:0xf bound_ctrl:1
	ds_read_b128 v[2:5], v98 offset:9216
	ds_read_b128 v[6:9], v98 offset:9472
	v_add_f32_dpp v104, v104, v104 quad_perm:[2,3,0,1] row_mask:0xf bank_mask:0xf bound_ctrl:1
	v_pk_mul_f32 v[36:37], v[36:37], v[40:41] op_sel_hi:[1,0]
	v_pk_mul_f32 v[38:39], v[38:39], v[40:41] op_sel_hi:[1,0]
	v_add_f32_dpp v104, v104, v104 row_half_mirror row_mask:0xf bank_mask:0xf bound_ctrl:1
	s_waitcnt lgkmcnt(5)
	v_pk_fma_f32 v[36:37], v[100:101], v[28:29], v[36:37]
	v_pk_fma_f32 v[38:39], v[102:103], v[30:31], v[38:39]
	v_add_f32_dpp v104, v104, v104 row_mirror row_mask:0xf bank_mask:0xf bound_ctrl:1
	v_pk_fma_f32 v[100:101], v[32:33], v[104:105], v[36:37] op_sel_hi:[1,0,1] neg_lo:[0,1,0] neg_hi:[0,1,0]
	v_pk_fma_f32 v[102:103], v[34:35], v[104:105], v[38:39] op_sel_hi:[1,0,1] neg_lo:[0,1,0] neg_hi:[0,1,0]
	v_pk_mul_f32 v[106:107], v[100:101], v[84:85]
	ds_read_b128 v[10:13], v98 offset:9728
	v_pk_fma_f32 v[106:107], v[102:103], v[86:87], v[106:107]
	s_waitcnt lgkmcnt(2)
	v_pk_mul_f32 v[104:105], v[100:101], v[2:3]
	v_add_f32_e32 v106, v106, v107
	ds_read_b128 v[18:21], v98 offset:10240
	v_pk_fma_f32 v[104:105], v[102:103], v[4:5], v[104:105]
	v_add_f32_dpp v106, v106, v106 quad_perm:[1,0,3,2] row_mask:0xf bank_mask:0xf bound_ctrl:1
	v_add_f32_e32 v104, v104, v105
	ds_write_b32 v97, v106 offset:2560
	ds_read_b32 v40, v99 offset:12032
	ds_read_b128 v[36:39], v98 offset:11520
	v_add_f32_dpp v104, v104, v104 quad_perm:[1,0,3,2] row_mask:0xf bank_mask:0xf bound_ctrl:1
	ds_read_b128 v[24:27], v98 offset:10752
	ds_read_b128 v[28:31], v98 offset:11008
	v_add_f32_dpp v104, v104, v104 quad_perm:[2,3,0,1] row_mask:0xf bank_mask:0xf bound_ctrl:1
	v_pk_mul_f32 v[14:15], v[14:15], v[22:23] op_sel_hi:[1,0]
	v_pk_mul_f32 v[16:17], v[16:17], v[22:23] op_sel_hi:[1,0]
	v_add_f32_dpp v104, v104, v104 row_half_mirror row_mask:0xf bank_mask:0xf bound_ctrl:1
	s_waitcnt lgkmcnt(5)
	v_pk_fma_f32 v[14:15], v[100:101], v[6:7], v[14:15]
	v_pk_fma_f32 v[16:17], v[102:103], v[8:9], v[16:17]
	v_add_f32_dpp v104, v104, v104 row_mirror row_mask:0xf bank_mask:0xf bound_ctrl:1
	v_pk_fma_f32 v[100:101], v[10:11], v[104:105], v[14:15] op_sel_hi:[1,0,1] neg_lo:[0,1,0] neg_hi:[0,1,0]
	v_pk_fma_f32 v[102:103], v[12:13], v[104:105], v[16:17] op_sel_hi:[1,0,1] neg_lo:[0,1,0] neg_hi:[0,1,0]
	v_pk_mul_f32 v[106:107], v[100:101], v[18:19]
	ds_read_b128 v[32:35], v98 offset:11264
	v_pk_fma_f32 v[106:107], v[102:103], v[20:21], v[106:107]
	s_waitcnt lgkmcnt(2)
	v_pk_mul_f32 v[104:105], v[100:101], v[24:25]
	v_add_f32_e32 v106, v106, v107
	ds_read_b128 v[84:87], v98 offset:11776
	v_pk_fma_f32 v[104:105], v[102:103], v[26:27], v[104:105]
	v_add_f32_dpp v106, v106, v106 quad_perm:[1,0,3,2] row_mask:0xf bank_mask:0xf bound_ctrl:1
	v_add_f32_e32 v104, v104, v105
	ds_write_b32 v97, v106 offset:3072
	ds_read_b32 v22, v99 offset:13568
	ds_read_b128 v[14:17], v98 offset:13056
	v_add_f32_dpp v104, v104, v104 quad_perm:[1,0,3,2] row_mask:0xf bank_mask:0xf bound_ctrl:1
	ds_read_b128 v[2:5], v98 offset:12288
	ds_read_b128 v[6:9], v98 offset:12544
	v_add_f32_dpp v104, v104, v104 quad_perm:[2,3,0,1] row_mask:0xf bank_mask:0xf bound_ctrl:1
	v_pk_mul_f32 v[36:37], v[36:37], v[40:41] op_sel_hi:[1,0]
	v_pk_mul_f32 v[38:39], v[38:39], v[40:41] op_sel_hi:[1,0]
	v_add_f32_dpp v104, v104, v104 row_half_mirror row_mask:0xf bank_mask:0xf bound_ctrl:1
	s_waitcnt lgkmcnt(5)
; DEVI void rwkv_scan_item(const Params& p, const int item, char* smem) {
;     ...
; #pragma unroll 2
;       for (int s = 0; s < 32; s += 2) {
;         RW_LD(s + 1, B)
;         __builtin_amdgcn_sched_barrier(0);
;         RW_STEP(s, A)
;         __builtin_amdgcn_sched_barrier(0);
;         if (s + 2 < 32) RW_LD(s + 2, A)
;         __builtin_amdgcn_sched_barrier(0);
;         RW_STEP(s + 1, B)
;         __builtin_amdgcn_sched_barrier(0);
;       }
	v_pk_fma_f32 v[36:37], v[100:101], v[28:29], v[36:37]
	v_pk_fma_f32 v[38:39], v[102:103], v[30:31], v[38:39]
	v_add_f32_dpp v104, v104, v104 row_mirror row_mask:0xf bank_mask:0xf bound_ctrl:1
	v_pk_fma_f32 v[100:101], v[32:33], v[104:105], v[36:37] op_sel_hi:[1,0,1] neg_lo:[0,1,0] neg_hi:[0,1,0]
	v_pk_fma_f32 v[102:103], v[34:35], v[104:105], v[38:39] op_sel_hi:[1,0,1] neg_lo:[0,1,0] neg_hi:[0,1,0]
	v_pk_mul_f32 v[106:107], v[100:101], v[84:85]
	ds_read_b128 v[10:13], v98 offset:12800
	v_pk_fma_f32 v[106:107], v[102:103], v[86:87], v[106:107]
	s_waitcnt lgkmcnt(2)
	v_pk_mul_f32 v[104:105], v[100:101], v[2:3]
	v_add_f32_e32 v106, v106, v107
	ds_read_b128 v[18:21], v98 offset:13312
	v_pk_fma_f32 v[104:105], v[102:103], v[4:5], v[104:105]
	v_add_f32_dpp v106, v106, v106 quad_perm:[1,0,3,2] row_mask:0xf bank_mask:0xf bound_ctrl:1
	v_add_f32_e32 v104, v104, v105
	ds_write_b32 v97, v106 offset:3584
	ds_read_b32 v40, v99 offset:15104
	ds_read_b128 v[36:39], v98 offset:14592
	v_add_f32_dpp v104, v104, v104 quad_perm:[1,0,3,2] row_mask:0xf bank_mask:0xf bound_ctrl:1
	ds_read_b128 v[24:27], v98 offset:13824
	ds_read_b128 v[28:31], v98 offset:14080
	v_add_f32_dpp v104, v104, v104 quad_perm:[2,3,0,1] row_mask:0xf bank_mask:0xf bound_ctrl:1
	v_pk_mul_f32 v[14:15], v[14:15], v[22:23] op_sel_hi:[1,0]
	v_pk_mul_f32 v[16:17], v[16:17], v[22:23] op_sel_hi:[1,0]
	v_add_f32_dpp v104, v104, v104 row_half_mirror row_mask:0xf bank_mask:0xf bound_ctrl:1
	s_waitcnt lgkmcnt(5)
	v_pk_fma_f32 v[14:15], v[100:101], v[6:7], v[14:15]
	v_pk_fma_f32 v[16:17], v[102:103], v[8:9], v[16:17]
	v_add_f32_dpp v104, v104, v104 row_mirror row_mask:0xf bank_mask:0xf bound_ctrl:1
	v_pk_fma_f32 v[100:101], v[10:11], v[104:105], v[14:15] op_sel_hi:[1,0,1] neg_lo:[0,1,0] neg_hi:[0,1,0]
	v_pk_fma_f32 v[102:103], v[12:13], v[104:105], v[16:17] op_sel_hi:[1,0,1] neg_lo:[0,1,0] neg_hi:[0,1,0]
	v_pk_mul_f32 v[106:107], v[100:101], v[18:19]
	ds_read_b128 v[32:35], v98 offset:14336
	v_pk_fma_f32 v[106:107], v[102:103], v[20:21], v[106:107]
	s_waitcnt lgkmcnt(2)
	v_pk_mul_f32 v[104:105], v[100:101], v[24:25]
	v_add_f32_e32 v106, v106, v107
	ds_read_b128 v[84:87], v98 offset:14848
	v_pk_fma_f32 v[104:105], v[102:103], v[26:27], v[104:105]
	v_add_f32_dpp v106, v106, v106 quad_perm:[1,0,3,2] row_mask:0xf bank_mask:0xf bound_ctrl:1
	v_add_f32_e32 v104, v104, v105
	ds_write_b32 v97, v106 offset:4096
	ds_read_b32 v22, v99 offset:16640
	ds_read_b128 v[14:17], v98 offset:16128
	v_add_f32_dpp v104, v104, v104 quad_perm:[1,0,3,2] row_mask:0xf bank_mask:0xf bound_ctrl:1
	ds_read_b128 v[2:5], v98 offset:15360
	ds_read_b128 v[6:9], v98 offset:15616
	v_add_f32_dpp v104, v104, v104 quad_perm:[2,3,0,1] row_mask:0xf bank_mask:0xf bound_ctrl:1
	v_pk_mul_f32 v[36:37], v[36:37], v[40:41] op_sel_hi:[1,0]
	v_pk_mul_f32 v[38:39], v[38:39], v[40:41] op_sel_hi:[1,0]
	v_add_f32_dpp v104, v104, v104 row_half_mirror row_mask:0xf bank_mask:0xf bound_ctrl:1
	s_waitcnt lgkmcnt(5)
	v_pk_fma_f32 v[36:37], v[100:101], v[28:29], v[36:37]
	v_pk_fma_f32 v[38:39], v[102:103], v[30:31], v[38:39]
	v_add_f32_dpp v104, v104, v104 row_mirror row_mask:0xf bank_mask:0xf bound_ctrl:1
	v_pk_fma_f32 v[100:101], v[32:33], v[104:105], v[36:37] op_sel_hi:[1,0,1] neg_lo:[0,1,0] neg_hi:[0,1,0]
	v_pk_fma_f32 v[102:103], v[34:35], v[104:105], v[38:39] op_sel_hi:[1,0,1] neg_lo:[0,1,0] neg_hi:[0,1,0]
	v_pk_mul_f32 v[106:107], v[100:101], v[84:85]
	ds_read_b128 v[10:13], v98 offset:15872
	v_pk_fma_f32 v[106:107], v[102:103], v[86:87], v[106:107]
	s_waitcnt lgkmcnt(2)
	v_pk_mul_f32 v[104:105], v[100:101], v[2:3]
	v_add_f32_e32 v106, v106, v107
	ds_read_b128 v[18:21], v98 offset:16384
	v_pk_fma_f32 v[104:105], v[102:103], v[4:5], v[104:105]
	v_add_f32_dpp v106, v106, v106 quad_perm:[1,0,3,2] row_mask:0xf bank_mask:0xf bound_ctrl:1
	v_add_f32_e32 v104, v104, v105
	ds_write_b32 v97, v106 offset:4608
	ds_read_b32 v40, v99 offset:18176
	ds_read_b128 v[36:39], v98 offset:17664
	v_add_f32_dpp v104, v104, v104 quad_perm:[1,0,3,2] row_mask:0xf bank_mask:0xf bound_ctrl:1
	ds_read_b128 v[24:27], v98 offset:16896
	ds_read_b128 v[28:31], v98 offset:17152
	v_add_f32_dpp v104, v104, v104 quad_perm:[2,3,0,1] row_mask:0xf bank_mask:0xf bound_ctrl:1
	v_pk_mul_f32 v[14:15], v[14:15], v[22:23] op_sel_hi:[1,0]
	v_pk_mul_f32 v[16:17], v[16:17], v[22:23] op_sel_hi:[1,0]
	v_add_f32_dpp v104, v104, v104 row_half_mirror row_mask:0xf bank_mask:0xf bound_ctrl:1
	s_waitcnt lgkmcnt(5)
	v_pk_fma_f32 v[14:15], v[100:101], v[6:7], v[14:15]
	v_pk_fma_f32 v[16:17], v[102:103], v[8:9], v[16:17]
	v_add_f32_dpp v104, v104, v104 row_mirror row_mask:0xf bank_mask:0xf bound_ctrl:1
	v_pk_fma_f32 v[100:101], v[10:11], v[104:105], v[14:15] op_sel_hi:[1,0,1] neg_lo:[0,1,0] neg_hi:[0,1,0]
	v_pk_fma_f32 v[102:103], v[12:13], v[104:105], v[16:17] op_sel_hi:[1,0,1] neg_lo:[0,1,0] neg_hi:[0,1,0]
	v_pk_mul_f32 v[106:107], v[100:101], v[18:19]
	ds_read_b128 v[32:35], v98 offset:17408
	v_pk_fma_f32 v[106:107], v[102:103], v[20:21], v[106:107]
	s_waitcnt lgkmcnt(2)
	v_pk_mul_f32 v[104:105], v[100:101], v[24:25]
	v_add_f32_e32 v106, v106, v107
	ds_read_b128 v[84:87], v98 offset:17920
	v_pk_fma_f32 v[104:105], v[102:103], v[26:27], v[104:105]
	v_add_f32_dpp v106, v106, v106 quad_perm:[1,0,3,2] row_mask:0xf bank_mask:0xf bound_ctrl:1
	v_add_f32_e32 v104, v104, v105
	ds_write_b32 v97, v106 offset:5120
	ds_read_b32 v22, v99 offset:19712
	ds_read_b128 v[14:17], v98 offset:19200
	v_add_f32_dpp v104, v104, v104 quad_perm:[1,0,3,2] row_mask:0xf bank_mask:0xf bound_ctrl:1
	ds_read_b128 v[2:5], v98 offset:18432
	ds_read_b128 v[6:9], v98 offset:18688
	v_add_f32_dpp v104, v104, v104 quad_perm:[2,3,0,1] row_mask:0xf bank_mask:0xf bound_ctrl:1
	v_pk_mul_f32 v[36:37], v[36:37], v[40:41] op_sel_hi:[1,0]
	v_pk_mul_f32 v[38:39], v[38:39], v[40:41] op_sel_hi:[1,0]
	v_add_f32_dpp v104, v104, v104 row_half_mirror row_mask:0xf bank_mask:0xf bound_ctrl:1
	s_waitcnt lgkmcnt(5)
; DEVI void rwkv_scan_item(const Params& p, const int item, char* smem) {
;     ...
; #pragma unroll 2
;       for (int s = 0; s < 32; s += 2) {
;         RW_LD(s + 1, B)
;         __builtin_amdgcn_sched_barrier(0);
;         RW_STEP(s, A)
;         __builtin_amdgcn_sched_barrier(0);
;         if (s + 2 < 32) RW_LD(s + 2, A)
;         __builtin_amdgcn_sched_barrier(0);
;         RW_STEP(s + 1, B)
;         __builtin_amdgcn_sched_barrier(0);
;       }
	v_pk_fma_f32 v[36:37], v[100:101], v[28:29], v[36:37]
	v_pk_fma_f32 v[38:39], v[102:103], v[30:31], v[38:39]
	v_add_f32_dpp v104, v104, v104 row_mirror row_mask:0xf bank_mask:0xf bound_ctrl:1
	v_pk_fma_f32 v[100:101], v[32:33], v[104:105], v[36:37] op_sel_hi:[1,0,1] neg_lo:[0,1,0] neg_hi:[0,1,0]
	v_pk_fma_f32 v[102:103], v[34:35], v[104:105], v[38:39] op_sel_hi:[1,0,1] neg_lo:[0,1,0] neg_hi:[0,1,0]
	v_pk_mul_f32 v[106:107], v[100:101], v[84:85]
	ds_read_b128 v[10:13], v98 offset:18944
	v_pk_fma_f32 v[106:107], v[102:103], v[86:87], v[106:107]
	s_waitcnt lgkmcnt(2)
	v_pk_mul_f32 v[104:105], v[100:101], v[2:3]
	v_add_f32_e32 v106, v106, v107
	ds_read_b128 v[18:21], v98 offset:19456
	v_pk_fma_f32 v[104:105], v[102:103], v[4:5], v[104:105]
	v_add_f32_dpp v106, v106, v106 quad_perm:[1,0,3,2] row_mask:0xf bank_mask:0xf bound_ctrl:1
	v_add_f32_e32 v104, v104, v105
	ds_write_b32 v97, v106 offset:5632
	ds_read_b32 v40, v99 offset:21248
	ds_read_b128 v[36:39], v98 offset:20736
	v_add_f32_dpp v104, v104, v104 quad_perm:[1,0,3,2] row_mask:0xf bank_mask:0xf bound_ctrl:1
	ds_read_b128 v[24:27], v98 offset:19968
	ds_read_b128 v[28:31], v98 offset:20224
	v_add_f32_dpp v104, v104, v104 quad_perm:[2,3,0,1] row_mask:0xf bank_mask:0xf bound_ctrl:1
	v_pk_mul_f32 v[14:15], v[14:15], v[22:23] op_sel_hi:[1,0]
	v_pk_mul_f32 v[16:17], v[16:17], v[22:23] op_sel_hi:[1,0]
	v_add_f32_dpp v104, v104, v104 row_half_mirror row_mask:0xf bank_mask:0xf bound_ctrl:1
	s_waitcnt lgkmcnt(5)
	v_pk_fma_f32 v[14:15], v[100:101], v[6:7], v[14:15]
	v_pk_fma_f32 v[16:17], v[102:103], v[8:9], v[16:17]
	v_add_f32_dpp v104, v104, v104 row_mirror row_mask:0xf bank_mask:0xf bound_ctrl:1
	v_pk_fma_f32 v[100:101], v[10:11], v[104:105], v[14:15] op_sel_hi:[1,0,1] neg_lo:[0,1,0] neg_hi:[0,1,0]
	v_pk_fma_f32 v[102:103], v[12:13], v[104:105], v[16:17] op_sel_hi:[1,0,1] neg_lo:[0,1,0] neg_hi:[0,1,0]
	v_pk_mul_f32 v[106:107], v[100:101], v[18:19]
	ds_read_b128 v[32:35], v98 offset:20480
	v_pk_fma_f32 v[106:107], v[102:103], v[20:21], v[106:107]
	s_waitcnt lgkmcnt(2)
	v_pk_mul_f32 v[104:105], v[100:101], v[24:25]
	v_add_f32_e32 v106, v106, v107
	ds_read_b128 v[84:87], v98 offset:20992
	v_pk_fma_f32 v[104:105], v[102:103], v[26:27], v[104:105]
	v_add_f32_dpp v106, v106, v106 quad_perm:[1,0,3,2] row_mask:0xf bank_mask:0xf bound_ctrl:1
	v_add_f32_e32 v104, v104, v105
	ds_write_b32 v97, v106 offset:6144
	ds_read_b32 v22, v99 offset:22784
	ds_read_b128 v[14:17], v98 offset:22272
	v_add_f32_dpp v104, v104, v104 quad_perm:[1,0,3,2] row_mask:0xf bank_mask:0xf bound_ctrl:1
	ds_read_b128 v[2:5], v98 offset:21504
	ds_read_b128 v[6:9], v98 offset:21760
	v_add_f32_dpp v104, v104, v104 quad_perm:[2,3,0,1] row_mask:0xf bank_mask:0xf bound_ctrl:1
	v_pk_mul_f32 v[36:37], v[36:37], v[40:41] op_sel_hi:[1,0]
	v_pk_mul_f32 v[38:39], v[38:39], v[40:41] op_sel_hi:[1,0]
	v_add_f32_dpp v104, v104, v104 row_half_mirror row_mask:0xf bank_mask:0xf bound_ctrl:1
	s_waitcnt lgkmcnt(5)
	v_pk_fma_f32 v[36:37], v[100:101], v[28:29], v[36:37]
	v_pk_fma_f32 v[38:39], v[102:103], v[30:31], v[38:39]
	v_add_f32_dpp v104, v104, v104 row_mirror row_mask:0xf bank_mask:0xf bound_ctrl:1
	v_pk_fma_f32 v[100:101], v[32:33], v[104:105], v[36:37] op_sel_hi:[1,0,1] neg_lo:[0,1,0] neg_hi:[0,1,0]
	v_pk_fma_f32 v[102:103], v[34:35], v[104:105], v[38:39] op_sel_hi:[1,0,1] neg_lo:[0,1,0] neg_hi:[0,1,0]
	v_pk_mul_f32 v[106:107], v[100:101], v[84:85]
	ds_read_b128 v[10:13], v98 offset:22016
	v_pk_fma_f32 v[106:107], v[102:103], v[86:87], v[106:107]
	s_waitcnt lgkmcnt(2)
	v_pk_mul_f32 v[104:105], v[100:101], v[2:3]
	v_add_f32_e32 v106, v106, v107
	ds_read_b128 v[18:21], v98 offset:22528
	v_pk_fma_f32 v[104:105], v[102:103], v[4:5], v[104:105]
	v_add_f32_dpp v106, v106, v106 quad_perm:[1,0,3,2] row_mask:0xf bank_mask:0xf bound_ctrl:1
	v_add_f32_e32 v104, v104, v105
	ds_write_b32 v97, v106 offset:6656
	ds_read_b32 v40, v99 offset:24320
	ds_read_b128 v[36:39], v98 offset:23808
	v_add_f32_dpp v104, v104, v104 quad_perm:[1,0,3,2] row_mask:0xf bank_mask:0xf bound_ctrl:1
	ds_read_b128 v[24:27], v98 offset:23040
	ds_read_b128 v[28:31], v98 offset:23296
	v_add_f32_dpp v104, v104, v104 quad_perm:[2,3,0,1] row_mask:0xf bank_mask:0xf bound_ctrl:1
	v_pk_mul_f32 v[14:15], v[14:15], v[22:23] op_sel_hi:[1,0]
	v_pk_mul_f32 v[16:17], v[16:17], v[22:23] op_sel_hi:[1,0]
	v_add_f32_dpp v104, v104, v104 row_half_mirror row_mask:0xf bank_mask:0xf bound_ctrl:1
	s_waitcnt lgkmcnt(5)
	v_pk_fma_f32 v[14:15], v[100:101], v[6:7], v[14:15]
	v_pk_fma_f32 v[16:17], v[102:103], v[8:9], v[16:17]
	v_add_f32_dpp v104, v104, v104 row_mirror row_mask:0xf bank_mask:0xf bound_ctrl:1
	v_pk_fma_f32 v[100:101], v[10:11], v[104:105], v[14:15] op_sel_hi:[1,0,1] neg_lo:[0,1,0] neg_hi:[0,1,0]
	v_pk_fma_f32 v[102:103], v[12:13], v[104:105], v[16:17] op_sel_hi:[1,0,1] neg_lo:[0,1,0] neg_hi:[0,1,0]
	v_pk_mul_f32 v[106:107], v[100:101], v[18:19]
	ds_read_b128 v[32:35], v98 offset:23552
	v_pk_fma_f32 v[106:107], v[102:103], v[20:21], v[106:107]
	s_waitcnt lgkmcnt(2)
	v_pk_mul_f32 v[104:105], v[100:101], v[24:25]
	v_add_f32_e32 v106, v106, v107
	ds_read_b128 v[84:87], v98 offset:24064
	v_pk_fma_f32 v[104:105], v[102:103], v[26:27], v[104:105]
	v_add_f32_dpp v106, v106, v106 quad_perm:[1,0,3,2] row_mask:0xf bank_mask:0xf bound_ctrl:1
	v_add_f32_e32 v104, v104, v105
	ds_write_b32 v97, v106 offset:7168
	ds_read_b32 v22, v99 offset:25856
	ds_read_b128 v[14:17], v98 offset:25344
	v_add_f32_dpp v104, v104, v104 quad_perm:[1,0,3,2] row_mask:0xf bank_mask:0xf bound_ctrl:1
	ds_read_b128 v[2:5], v98 offset:24576
	ds_read_b128 v[6:9], v98 offset:24832
	v_add_f32_dpp v104, v104, v104 quad_perm:[2,3,0,1] row_mask:0xf bank_mask:0xf bound_ctrl:1
	v_pk_mul_f32 v[36:37], v[36:37], v[40:41] op_sel_hi:[1,0]
	v_pk_mul_f32 v[38:39], v[38:39], v[40:41] op_sel_hi:[1,0]
	v_add_f32_dpp v104, v104, v104 row_half_mirror row_mask:0xf bank_mask:0xf bound_ctrl:1
	s_waitcnt lgkmcnt(5)
; DEVI void rwkv_scan_item(const Params& p, const int item, char* smem) {
;     ...
; #pragma unroll 2
;       for (int s = 0; s < 32; s += 2) {
;         RW_LD(s + 1, B)
;         __builtin_amdgcn_sched_barrier(0);
;         RW_STEP(s, A)
;         __builtin_amdgcn_sched_barrier(0);
;         if (s + 2 < 32) RW_LD(s + 2, A)
;         __builtin_amdgcn_sched_barrier(0);
;         RW_STEP(s + 1, B)
;         __builtin_amdgcn_sched_barrier(0);
;       }
	v_pk_fma_f32 v[36:37], v[100:101], v[28:29], v[36:37]
	v_pk_fma_f32 v[38:39], v[102:103], v[30:31], v[38:39]
	v_add_f32_dpp v104, v104, v104 row_mirror row_mask:0xf bank_mask:0xf bound_ctrl:1
	v_pk_fma_f32 v[100:101], v[32:33], v[104:105], v[36:37] op_sel_hi:[1,0,1] neg_lo:[0,1,0] neg_hi:[0,1,0]
	v_pk_fma_f32 v[102:103], v[34:35], v[104:105], v[38:39] op_sel_hi:[1,0,1] neg_lo:[0,1,0] neg_hi:[0,1,0]
	v_pk_mul_f32 v[106:107], v[100:101], v[84:85]
	ds_read_b128 v[10:13], v98 offset:25088
	v_pk_fma_f32 v[106:107], v[102:103], v[86:87], v[106:107]
	s_waitcnt lgkmcnt(2)
	v_pk_mul_f32 v[104:105], v[100:101], v[2:3]
	v_add_f32_e32 v106, v106, v107
	ds_read_b128 v[18:21], v98 offset:25600
	v_pk_fma_f32 v[104:105], v[102:103], v[4:5], v[104:105]
	v_add_f32_dpp v106, v106, v106 quad_perm:[1,0,3,2] row_mask:0xf bank_mask:0xf bound_ctrl:1
	v_add_f32_e32 v104, v104, v105
	ds_write_b32 v97, v106 offset:7680
	ds_read_b32 v40, v99 offset:27392
	ds_read_b128 v[36:39], v98 offset:26880
	v_add_f32_dpp v104, v104, v104 quad_perm:[1,0,3,2] row_mask:0xf bank_mask:0xf bound_ctrl:1
	ds_read_b128 v[24:27], v98 offset:26112
	ds_read_b128 v[28:31], v98 offset:26368
	v_add_f32_dpp v104, v104, v104 quad_perm:[2,3,0,1] row_mask:0xf bank_mask:0xf bound_ctrl:1
	v_pk_mul_f32 v[14:15], v[14:15], v[22:23] op_sel_hi:[1,0]
	v_pk_mul_f32 v[16:17], v[16:17], v[22:23] op_sel_hi:[1,0]
	v_add_f32_dpp v104, v104, v104 row_half_mirror row_mask:0xf bank_mask:0xf bound_ctrl:1
	s_waitcnt lgkmcnt(5)
	v_pk_fma_f32 v[14:15], v[100:101], v[6:7], v[14:15]
	v_pk_fma_f32 v[16:17], v[102:103], v[8:9], v[16:17]
	v_add_f32_dpp v104, v104, v104 row_mirror row_mask:0xf bank_mask:0xf bound_ctrl:1
	v_pk_fma_f32 v[100:101], v[10:11], v[104:105], v[14:15] op_sel_hi:[1,0,1] neg_lo:[0,1,0] neg_hi:[0,1,0]
	v_pk_fma_f32 v[102:103], v[12:13], v[104:105], v[16:17] op_sel_hi:[1,0,1] neg_lo:[0,1,0] neg_hi:[0,1,0]
	v_pk_mul_f32 v[106:107], v[100:101], v[18:19]
	ds_read_b128 v[32:35], v98 offset:26624
	v_pk_fma_f32 v[106:107], v[102:103], v[20:21], v[106:107]
	s_waitcnt lgkmcnt(2)
	v_pk_mul_f32 v[104:105], v[100:101], v[24:25]
	v_add_f32_e32 v106, v106, v107
	ds_read_b128 v[84:87], v98 offset:27136
	v_pk_fma_f32 v[104:105], v[102:103], v[26:27], v[104:105]
	v_add_f32_dpp v106, v106, v106 quad_perm:[1,0,3,2] row_mask:0xf bank_mask:0xf bound_ctrl:1
	v_add_f32_e32 v104, v104, v105
	ds_write_b32 v97, v106 offset:8192
	ds_read_b32 v22, v99 offset:28928
	ds_read_b128 v[14:17], v98 offset:28416
	v_add_f32_dpp v104, v104, v104 quad_perm:[1,0,3,2] row_mask:0xf bank_mask:0xf bound_ctrl:1
	ds_read_b128 v[2:5], v98 offset:27648
	ds_read_b128 v[6:9], v98 offset:27904
	v_add_f32_dpp v104, v104, v104 quad_perm:[2,3,0,1] row_mask:0xf bank_mask:0xf bound_ctrl:1
	v_pk_mul_f32 v[36:37], v[36:37], v[40:41] op_sel_hi:[1,0]
	v_pk_mul_f32 v[38:39], v[38:39], v[40:41] op_sel_hi:[1,0]
	v_add_f32_dpp v104, v104, v104 row_half_mirror row_mask:0xf bank_mask:0xf bound_ctrl:1
	s_waitcnt lgkmcnt(5)
	v_pk_fma_f32 v[36:37], v[100:101], v[28:29], v[36:37]
	v_pk_fma_f32 v[38:39], v[102:103], v[30:31], v[38:39]
	v_add_f32_dpp v104, v104, v104 row_mirror row_mask:0xf bank_mask:0xf bound_ctrl:1
	v_pk_fma_f32 v[100:101], v[32:33], v[104:105], v[36:37] op_sel_hi:[1,0,1] neg_lo:[0,1,0] neg_hi:[0,1,0]
	v_pk_fma_f32 v[102:103], v[34:35], v[104:105], v[38:39] op_sel_hi:[1,0,1] neg_lo:[0,1,0] neg_hi:[0,1,0]
	v_pk_mul_f32 v[106:107], v[100:101], v[84:85]
	ds_read_b128 v[10:13], v98 offset:28160
	v_pk_fma_f32 v[106:107], v[102:103], v[86:87], v[106:107]
	s_waitcnt lgkmcnt(2)
	v_pk_mul_f32 v[104:105], v[100:101], v[2:3]
	v_add_f32_e32 v106, v106, v107
	ds_read_b128 v[18:21], v98 offset:28672
	v_pk_fma_f32 v[104:105], v[102:103], v[4:5], v[104:105]
	v_add_f32_dpp v106, v106, v106 quad_perm:[1,0,3,2] row_mask:0xf bank_mask:0xf bound_ctrl:1
	v_add_f32_e32 v104, v104, v105
	ds_write_b32 v97, v106 offset:8704
	ds_read_b32 v40, v99 offset:30464
	ds_read_b128 v[36:39], v98 offset:29952
	v_add_f32_dpp v104, v104, v104 quad_perm:[1,0,3,2] row_mask:0xf bank_mask:0xf bound_ctrl:1
	ds_read_b128 v[24:27], v98 offset:29184
	ds_read_b128 v[28:31], v98 offset:29440
	v_add_f32_dpp v104, v104, v104 quad_perm:[2,3,0,1] row_mask:0xf bank_mask:0xf bound_ctrl:1
	v_pk_mul_f32 v[14:15], v[14:15], v[22:23] op_sel_hi:[1,0]
	v_pk_mul_f32 v[16:17], v[16:17], v[22:23] op_sel_hi:[1,0]
	v_add_f32_dpp v104, v104, v104 row_half_mirror row_mask:0xf bank_mask:0xf bound_ctrl:1
	s_waitcnt lgkmcnt(5)
	v_pk_fma_f32 v[14:15], v[100:101], v[6:7], v[14:15]
	v_pk_fma_f32 v[16:17], v[102:103], v[8:9], v[16:17]
	v_add_f32_dpp v104, v104, v104 row_mirror row_mask:0xf bank_mask:0xf bound_ctrl:1
	v_pk_fma_f32 v[100:101], v[10:11], v[104:105], v[14:15] op_sel_hi:[1,0,1] neg_lo:[0,1,0] neg_hi:[0,1,0]
	v_pk_fma_f32 v[102:103], v[12:13], v[104:105], v[16:17] op_sel_hi:[1,0,1] neg_lo:[0,1,0] neg_hi:[0,1,0]
	v_pk_mul_f32 v[106:107], v[100:101], v[18:19]
	ds_read_b128 v[32:35], v98 offset:29696
	v_pk_fma_f32 v[106:107], v[102:103], v[20:21], v[106:107]
	s_waitcnt lgkmcnt(2)
	v_pk_mul_f32 v[104:105], v[100:101], v[24:25]
	v_add_f32_e32 v106, v106, v107
	ds_read_b128 v[84:87], v98 offset:30208
	v_pk_fma_f32 v[104:105], v[102:103], v[26:27], v[104:105]
	v_add_f32_dpp v106, v106, v106 quad_perm:[1,0,3,2] row_mask:0xf bank_mask:0xf bound_ctrl:1
	v_add_f32_e32 v104, v104, v105
	ds_write_b32 v97, v106 offset:9216
	ds_read_b32 v22, v99 offset:32000
	ds_read_b128 v[14:17], v98 offset:31488
	v_add_f32_dpp v104, v104, v104 quad_perm:[1,0,3,2] row_mask:0xf bank_mask:0xf bound_ctrl:1
	ds_read_b128 v[2:5], v98 offset:30720
	ds_read_b128 v[6:9], v98 offset:30976
	v_add_f32_dpp v104, v104, v104 quad_perm:[2,3,0,1] row_mask:0xf bank_mask:0xf bound_ctrl:1
	v_pk_mul_f32 v[36:37], v[36:37], v[40:41] op_sel_hi:[1,0]
	v_pk_mul_f32 v[38:39], v[38:39], v[40:41] op_sel_hi:[1,0]
	v_add_f32_dpp v104, v104, v104 row_half_mirror row_mask:0xf bank_mask:0xf bound_ctrl:1
	s_waitcnt lgkmcnt(5)
; DEVI void rwkv_scan_item(const Params& p, const int item, char* smem) {
;     ...
; #pragma unroll 2
;       for (int s = 0; s < 32; s += 2) {
;         RW_LD(s + 1, B)
;         __builtin_amdgcn_sched_barrier(0);
;         RW_STEP(s, A)
;         __builtin_amdgcn_sched_barrier(0);
;         if (s + 2 < 32) RW_LD(s + 2, A)
;         __builtin_amdgcn_sched_barrier(0);
;         RW_STEP(s + 1, B)
;         __builtin_amdgcn_sched_barrier(0);
;       }
	v_pk_fma_f32 v[36:37], v[100:101], v[28:29], v[36:37]
	v_pk_fma_f32 v[38:39], v[102:103], v[30:31], v[38:39]
	v_add_f32_dpp v104, v104, v104 row_mirror row_mask:0xf bank_mask:0xf bound_ctrl:1
	v_pk_fma_f32 v[100:101], v[32:33], v[104:105], v[36:37] op_sel_hi:[1,0,1] neg_lo:[0,1,0] neg_hi:[0,1,0]
	v_pk_fma_f32 v[102:103], v[34:35], v[104:105], v[38:39] op_sel_hi:[1,0,1] neg_lo:[0,1,0] neg_hi:[0,1,0]
	v_pk_mul_f32 v[106:107], v[100:101], v[84:85]
	ds_read_b128 v[10:13], v98 offset:31232
	v_pk_fma_f32 v[106:107], v[102:103], v[86:87], v[106:107]
	s_waitcnt lgkmcnt(2)
	v_pk_mul_f32 v[104:105], v[100:101], v[2:3]
	v_add_f32_e32 v106, v106, v107
	ds_read_b128 v[18:21], v98 offset:31744
	v_pk_fma_f32 v[104:105], v[102:103], v[4:5], v[104:105]
	v_add_f32_dpp v106, v106, v106 quad_perm:[1,0,3,2] row_mask:0xf bank_mask:0xf bound_ctrl:1
	v_add_f32_e32 v104, v104, v105
	ds_write_b32 v97, v106 offset:9728
	ds_read_b32 v40, v99 offset:33536
	ds_read_b128 v[36:39], v98 offset:33024
	v_add_f32_dpp v104, v104, v104 quad_perm:[1,0,3,2] row_mask:0xf bank_mask:0xf bound_ctrl:1
	ds_read_b128 v[24:27], v98 offset:32256
	ds_read_b128 v[28:31], v98 offset:32512
	v_add_f32_dpp v104, v104, v104 quad_perm:[2,3,0,1] row_mask:0xf bank_mask:0xf bound_ctrl:1
	v_pk_mul_f32 v[14:15], v[14:15], v[22:23] op_sel_hi:[1,0]
	v_pk_mul_f32 v[16:17], v[16:17], v[22:23] op_sel_hi:[1,0]
	v_add_f32_dpp v104, v104, v104 row_half_mirror row_mask:0xf bank_mask:0xf bound_ctrl:1
	s_waitcnt lgkmcnt(5)
	v_pk_fma_f32 v[14:15], v[100:101], v[6:7], v[14:15]
	v_pk_fma_f32 v[16:17], v[102:103], v[8:9], v[16:17]
	v_add_f32_dpp v104, v104, v104 row_mirror row_mask:0xf bank_mask:0xf bound_ctrl:1
	v_pk_fma_f32 v[100:101], v[10:11], v[104:105], v[14:15] op_sel_hi:[1,0,1] neg_lo:[0,1,0] neg_hi:[0,1,0]
	v_pk_fma_f32 v[102:103], v[12:13], v[104:105], v[16:17] op_sel_hi:[1,0,1] neg_lo:[0,1,0] neg_hi:[0,1,0]
	v_pk_mul_f32 v[106:107], v[100:101], v[18:19]
	ds_read_b128 v[32:35], v98 offset:32768
	v_pk_fma_f32 v[106:107], v[102:103], v[20:21], v[106:107]
	s_waitcnt lgkmcnt(2)
	v_pk_mul_f32 v[104:105], v[100:101], v[24:25]
	v_add_f32_e32 v106, v106, v107
	ds_read_b128 v[84:87], v98 offset:33280
	v_pk_fma_f32 v[104:105], v[102:103], v[26:27], v[104:105]
	v_add_f32_dpp v106, v106, v106 quad_perm:[1,0,3,2] row_mask:0xf bank_mask:0xf bound_ctrl:1
	v_add_f32_e32 v104, v104, v105
	ds_write_b32 v97, v106 offset:10240
	ds_read_b32 v22, v99 offset:35072
	ds_read_b128 v[14:17], v98 offset:34560
	v_add_f32_dpp v104, v104, v104 quad_perm:[1,0,3,2] row_mask:0xf bank_mask:0xf bound_ctrl:1
	ds_read_b128 v[2:5], v98 offset:33792
	ds_read_b128 v[6:9], v98 offset:34048
	v_add_f32_dpp v104, v104, v104 quad_perm:[2,3,0,1] row_mask:0xf bank_mask:0xf bound_ctrl:1
	v_pk_mul_f32 v[36:37], v[36:37], v[40:41] op_sel_hi:[1,0]
	v_pk_mul_f32 v[38:39], v[38:39], v[40:41] op_sel_hi:[1,0]
	v_add_f32_dpp v104, v104, v104 row_half_mirror row_mask:0xf bank_mask:0xf bound_ctrl:1
	s_waitcnt lgkmcnt(5)
	v_pk_fma_f32 v[36:37], v[100:101], v[28:29], v[36:37]
	v_pk_fma_f32 v[38:39], v[102:103], v[30:31], v[38:39]
	v_add_f32_dpp v104, v104, v104 row_mirror row_mask:0xf bank_mask:0xf bound_ctrl:1
	v_pk_fma_f32 v[100:101], v[32:33], v[104:105], v[36:37] op_sel_hi:[1,0,1] neg_lo:[0,1,0] neg_hi:[0,1,0]
	v_pk_fma_f32 v[102:103], v[34:35], v[104:105], v[38:39] op_sel_hi:[1,0,1] neg_lo:[0,1,0] neg_hi:[0,1,0]
	v_pk_mul_f32 v[106:107], v[100:101], v[84:85]
	ds_read_b128 v[10:13], v98 offset:34304
	v_pk_fma_f32 v[106:107], v[102:103], v[86:87], v[106:107]
	s_waitcnt lgkmcnt(2)
	v_pk_mul_f32 v[104:105], v[100:101], v[2:3]
	v_add_f32_e32 v106, v106, v107
	ds_read_b128 v[18:21], v98 offset:34816
	v_pk_fma_f32 v[104:105], v[102:103], v[4:5], v[104:105]
	v_add_f32_dpp v106, v106, v106 quad_perm:[1,0,3,2] row_mask:0xf bank_mask:0xf bound_ctrl:1
	v_add_f32_e32 v104, v104, v105
	ds_write_b32 v97, v106 offset:10752
	ds_read_b32 v40, v99 offset:36608
	ds_read_b128 v[36:39], v98 offset:36096
	v_add_f32_dpp v104, v104, v104 quad_perm:[1,0,3,2] row_mask:0xf bank_mask:0xf bound_ctrl:1
	ds_read_b128 v[24:27], v98 offset:35328
	ds_read_b128 v[28:31], v98 offset:35584
	v_add_f32_dpp v104, v104, v104 quad_perm:[2,3,0,1] row_mask:0xf bank_mask:0xf bound_ctrl:1
	v_pk_mul_f32 v[14:15], v[14:15], v[22:23] op_sel_hi:[1,0]
	v_pk_mul_f32 v[16:17], v[16:17], v[22:23] op_sel_hi:[1,0]
	v_add_f32_dpp v104, v104, v104 row_half_mirror row_mask:0xf bank_mask:0xf bound_ctrl:1
	s_waitcnt lgkmcnt(5)
	v_pk_fma_f32 v[14:15], v[100:101], v[6:7], v[14:15]
	v_pk_fma_f32 v[16:17], v[102:103], v[8:9], v[16:17]
	v_add_f32_dpp v104, v104, v104 row_mirror row_mask:0xf bank_mask:0xf bound_ctrl:1
	v_pk_fma_f32 v[100:101], v[10:11], v[104:105], v[14:15] op_sel_hi:[1,0,1] neg_lo:[0,1,0] neg_hi:[0,1,0]
	v_pk_fma_f32 v[102:103], v[12:13], v[104:105], v[16:17] op_sel_hi:[1,0,1] neg_lo:[0,1,0] neg_hi:[0,1,0]
	v_pk_mul_f32 v[106:107], v[100:101], v[18:19]
	ds_read_b128 v[32:35], v98 offset:35840
	v_pk_fma_f32 v[106:107], v[102:103], v[20:21], v[106:107]
	s_waitcnt lgkmcnt(2)
	v_pk_mul_f32 v[104:105], v[100:101], v[24:25]
	v_add_f32_e32 v106, v106, v107
	ds_read_b128 v[84:87], v98 offset:36352
	v_pk_fma_f32 v[104:105], v[102:103], v[26:27], v[104:105]
	v_add_f32_dpp v106, v106, v106 quad_perm:[1,0,3,2] row_mask:0xf bank_mask:0xf bound_ctrl:1
	v_add_f32_e32 v104, v104, v105
	ds_write_b32 v97, v106 offset:11264
	ds_read_b32 v22, v99 offset:38144
	ds_read_b128 v[14:17], v98 offset:37632
	v_add_f32_dpp v104, v104, v104 quad_perm:[1,0,3,2] row_mask:0xf bank_mask:0xf bound_ctrl:1
	ds_read_b128 v[2:5], v98 offset:36864
	ds_read_b128 v[6:9], v98 offset:37120
	v_add_f32_dpp v104, v104, v104 quad_perm:[2,3,0,1] row_mask:0xf bank_mask:0xf bound_ctrl:1
	v_pk_mul_f32 v[36:37], v[36:37], v[40:41] op_sel_hi:[1,0]
	v_pk_mul_f32 v[38:39], v[38:39], v[40:41] op_sel_hi:[1,0]
	v_add_f32_dpp v104, v104, v104 row_half_mirror row_mask:0xf bank_mask:0xf bound_ctrl:1
	s_waitcnt lgkmcnt(5)
; DEVI void rwkv_scan_item(const Params& p, const int item, char* smem) {
;     ...
; #pragma unroll 2
;       for (int s = 0; s < 32; s += 2) {
;         RW_LD(s + 1, B)
;         __builtin_amdgcn_sched_barrier(0);
;         RW_STEP(s, A)
;         __builtin_amdgcn_sched_barrier(0);
;         if (s + 2 < 32) RW_LD(s + 2, A)
;         __builtin_amdgcn_sched_barrier(0);
;         RW_STEP(s + 1, B)
;         __builtin_amdgcn_sched_barrier(0);
;       }
	v_pk_fma_f32 v[36:37], v[100:101], v[28:29], v[36:37]
	v_pk_fma_f32 v[38:39], v[102:103], v[30:31], v[38:39]
	v_add_f32_dpp v104, v104, v104 row_mirror row_mask:0xf bank_mask:0xf bound_ctrl:1
	v_pk_fma_f32 v[100:101], v[32:33], v[104:105], v[36:37] op_sel_hi:[1,0,1] neg_lo:[0,1,0] neg_hi:[0,1,0]
	v_pk_fma_f32 v[102:103], v[34:35], v[104:105], v[38:39] op_sel_hi:[1,0,1] neg_lo:[0,1,0] neg_hi:[0,1,0]
	v_pk_mul_f32 v[106:107], v[100:101], v[84:85]
	ds_read_b128 v[10:13], v98 offset:37376
	v_pk_fma_f32 v[106:107], v[102:103], v[86:87], v[106:107]
	s_waitcnt lgkmcnt(2)
	v_pk_mul_f32 v[104:105], v[100:101], v[2:3]
	v_add_f32_e32 v106, v106, v107
	ds_read_b128 v[18:21], v98 offset:37888
	v_pk_fma_f32 v[104:105], v[102:103], v[4:5], v[104:105]
	v_add_f32_dpp v106, v106, v106 quad_perm:[1,0,3,2] row_mask:0xf bank_mask:0xf bound_ctrl:1
	v_add_f32_e32 v104, v104, v105
	ds_write_b32 v97, v106 offset:11776
	ds_read_b32 v40, v99 offset:39680
	ds_read_b128 v[36:39], v98 offset:39168
	v_add_f32_dpp v104, v104, v104 quad_perm:[1,0,3,2] row_mask:0xf bank_mask:0xf bound_ctrl:1
	ds_read_b128 v[24:27], v98 offset:38400
	ds_read_b128 v[28:31], v98 offset:38656
	v_add_f32_dpp v104, v104, v104 quad_perm:[2,3,0,1] row_mask:0xf bank_mask:0xf bound_ctrl:1
	v_pk_mul_f32 v[14:15], v[14:15], v[22:23] op_sel_hi:[1,0]
	v_pk_mul_f32 v[16:17], v[16:17], v[22:23] op_sel_hi:[1,0]
	v_add_f32_dpp v104, v104, v104 row_half_mirror row_mask:0xf bank_mask:0xf bound_ctrl:1
	s_waitcnt lgkmcnt(5)
	v_pk_fma_f32 v[14:15], v[100:101], v[6:7], v[14:15]
	v_pk_fma_f32 v[16:17], v[102:103], v[8:9], v[16:17]
	v_add_f32_dpp v104, v104, v104 row_mirror row_mask:0xf bank_mask:0xf bound_ctrl:1
	v_pk_fma_f32 v[100:101], v[10:11], v[104:105], v[14:15] op_sel_hi:[1,0,1] neg_lo:[0,1,0] neg_hi:[0,1,0]
	v_pk_fma_f32 v[102:103], v[12:13], v[104:105], v[16:17] op_sel_hi:[1,0,1] neg_lo:[0,1,0] neg_hi:[0,1,0]
	v_pk_mul_f32 v[106:107], v[100:101], v[18:19]
	ds_read_b128 v[32:35], v98 offset:38912
	v_pk_fma_f32 v[106:107], v[102:103], v[20:21], v[106:107]
	s_waitcnt lgkmcnt(2)
	v_pk_mul_f32 v[104:105], v[100:101], v[24:25]
	v_add_f32_e32 v106, v106, v107
	ds_read_b128 v[84:87], v98 offset:39424
	v_pk_fma_f32 v[104:105], v[102:103], v[26:27], v[104:105]
	v_add_f32_dpp v106, v106, v106 quad_perm:[1,0,3,2] row_mask:0xf bank_mask:0xf bound_ctrl:1
	v_add_f32_e32 v104, v104, v105
	ds_write_b32 v97, v106 offset:12288
	ds_read_b32 v22, v99 offset:41216
	ds_read_b128 v[14:17], v98 offset:40704
	v_add_f32_dpp v104, v104, v104 quad_perm:[1,0,3,2] row_mask:0xf bank_mask:0xf bound_ctrl:1
	ds_read_b128 v[2:5], v98 offset:39936
	ds_read_b128 v[6:9], v98 offset:40192
	v_add_f32_dpp v104, v104, v104 quad_perm:[2,3,0,1] row_mask:0xf bank_mask:0xf bound_ctrl:1
	v_pk_mul_f32 v[36:37], v[36:37], v[40:41] op_sel_hi:[1,0]
	v_pk_mul_f32 v[38:39], v[38:39], v[40:41] op_sel_hi:[1,0]
	v_add_f32_dpp v104, v104, v104 row_half_mirror row_mask:0xf bank_mask:0xf bound_ctrl:1
	s_waitcnt lgkmcnt(5)
	v_pk_fma_f32 v[36:37], v[100:101], v[28:29], v[36:37]
	v_pk_fma_f32 v[38:39], v[102:103], v[30:31], v[38:39]
	v_add_f32_dpp v104, v104, v104 row_mirror row_mask:0xf bank_mask:0xf bound_ctrl:1
	v_pk_fma_f32 v[100:101], v[32:33], v[104:105], v[36:37] op_sel_hi:[1,0,1] neg_lo:[0,1,0] neg_hi:[0,1,0]
	v_pk_fma_f32 v[102:103], v[34:35], v[104:105], v[38:39] op_sel_hi:[1,0,1] neg_lo:[0,1,0] neg_hi:[0,1,0]
	v_pk_mul_f32 v[106:107], v[100:101], v[84:85]
	ds_read_b128 v[10:13], v98 offset:40448
	v_pk_fma_f32 v[106:107], v[102:103], v[86:87], v[106:107]
	s_waitcnt lgkmcnt(2)
	v_pk_mul_f32 v[104:105], v[100:101], v[2:3]
	v_add_f32_e32 v106, v106, v107
	ds_read_b128 v[18:21], v98 offset:40960
	v_pk_fma_f32 v[104:105], v[102:103], v[4:5], v[104:105]
	v_add_f32_dpp v106, v106, v106 quad_perm:[1,0,3,2] row_mask:0xf bank_mask:0xf bound_ctrl:1
	v_add_f32_e32 v104, v104, v105
	ds_write_b32 v97, v106 offset:12800
	ds_read_b32 v40, v99 offset:42752
	ds_read_b128 v[36:39], v98 offset:42240
	v_add_f32_dpp v104, v104, v104 quad_perm:[1,0,3,2] row_mask:0xf bank_mask:0xf bound_ctrl:1
	ds_read_b128 v[24:27], v98 offset:41472
	ds_read_b128 v[28:31], v98 offset:41728
	v_add_f32_dpp v104, v104, v104 quad_perm:[2,3,0,1] row_mask:0xf bank_mask:0xf bound_ctrl:1
	v_pk_mul_f32 v[14:15], v[14:15], v[22:23] op_sel_hi:[1,0]
	v_pk_mul_f32 v[16:17], v[16:17], v[22:23] op_sel_hi:[1,0]
	v_add_f32_dpp v104, v104, v104 row_half_mirror row_mask:0xf bank_mask:0xf bound_ctrl:1
	s_waitcnt lgkmcnt(5)
	v_pk_fma_f32 v[14:15], v[100:101], v[6:7], v[14:15]
	v_pk_fma_f32 v[16:17], v[102:103], v[8:9], v[16:17]
	v_add_f32_dpp v104, v104, v104 row_mirror row_mask:0xf bank_mask:0xf bound_ctrl:1
	v_pk_fma_f32 v[100:101], v[10:11], v[104:105], v[14:15] op_sel_hi:[1,0,1] neg_lo:[0,1,0] neg_hi:[0,1,0]
	v_pk_fma_f32 v[102:103], v[12:13], v[104:105], v[16:17] op_sel_hi:[1,0,1] neg_lo:[0,1,0] neg_hi:[0,1,0]
	v_pk_mul_f32 v[106:107], v[100:101], v[18:19]
	ds_read_b128 v[32:35], v98 offset:41984
	v_pk_fma_f32 v[106:107], v[102:103], v[20:21], v[106:107]
	s_waitcnt lgkmcnt(2)
	v_pk_mul_f32 v[104:105], v[100:101], v[24:25]
	v_add_f32_e32 v106, v106, v107
	ds_read_b128 v[84:87], v98 offset:42496
	v_pk_fma_f32 v[104:105], v[102:103], v[26:27], v[104:105]
	v_add_f32_dpp v106, v106, v106 quad_perm:[1,0,3,2] row_mask:0xf bank_mask:0xf bound_ctrl:1
	v_add_f32_e32 v104, v104, v105
	ds_write_b32 v97, v106 offset:13312
	ds_read_b32 v22, v99 offset:44288
	ds_read_b128 v[14:17], v98 offset:43776
	v_add_f32_dpp v104, v104, v104 quad_perm:[1,0,3,2] row_mask:0xf bank_mask:0xf bound_ctrl:1
	ds_read_b128 v[2:5], v98 offset:43008
	ds_read_b128 v[6:9], v98 offset:43264
	v_add_f32_dpp v104, v104, v104 quad_perm:[2,3,0,1] row_mask:0xf bank_mask:0xf bound_ctrl:1
	v_pk_mul_f32 v[36:37], v[36:37], v[40:41] op_sel_hi:[1,0]
	v_pk_mul_f32 v[38:39], v[38:39], v[40:41] op_sel_hi:[1,0]
	v_add_f32_dpp v104, v104, v104 row_half_mirror row_mask:0xf bank_mask:0xf bound_ctrl:1
	s_waitcnt lgkmcnt(5)
; DEVI void rwkv_scan_item(const Params& p, const int item, char* smem) {
;     ...
; #pragma unroll 2
;       for (int s = 0; s < 32; s += 2) {
;         RW_LD(s + 1, B)
;         __builtin_amdgcn_sched_barrier(0);
;         RW_STEP(s, A)
;         __builtin_amdgcn_sched_barrier(0);
;         if (s + 2 < 32) RW_LD(s + 2, A)
;         __builtin_amdgcn_sched_barrier(0);
;         RW_STEP(s + 1, B)
;         __builtin_amdgcn_sched_barrier(0);
;       }
	v_pk_fma_f32 v[36:37], v[100:101], v[28:29], v[36:37]
	v_pk_fma_f32 v[38:39], v[102:103], v[30:31], v[38:39]
	v_add_f32_dpp v104, v104, v104 row_mirror row_mask:0xf bank_mask:0xf bound_ctrl:1
	v_pk_fma_f32 v[100:101], v[32:33], v[104:105], v[36:37] op_sel_hi:[1,0,1] neg_lo:[0,1,0] neg_hi:[0,1,0]
	v_pk_fma_f32 v[102:103], v[34:35], v[104:105], v[38:39] op_sel_hi:[1,0,1] neg_lo:[0,1,0] neg_hi:[0,1,0]
	v_pk_mul_f32 v[106:107], v[100:101], v[84:85]
	ds_read_b128 v[10:13], v98 offset:43520
	v_pk_fma_f32 v[106:107], v[102:103], v[86:87], v[106:107]
	s_waitcnt lgkmcnt(2)
	v_pk_mul_f32 v[104:105], v[100:101], v[2:3]
	v_add_f32_e32 v106, v106, v107
	ds_read_b128 v[18:21], v98 offset:44032
	v_pk_fma_f32 v[104:105], v[102:103], v[4:5], v[104:105]
	v_add_f32_dpp v106, v106, v106 quad_perm:[1,0,3,2] row_mask:0xf bank_mask:0xf bound_ctrl:1
	v_add_f32_e32 v104, v104, v105
	ds_write_b32 v97, v106 offset:13824
	ds_read_b32 v40, v99 offset:45824
	ds_read_b128 v[36:39], v98 offset:45312
	v_add_f32_dpp v104, v104, v104 quad_perm:[1,0,3,2] row_mask:0xf bank_mask:0xf bound_ctrl:1
	ds_read_b128 v[24:27], v98 offset:44544
	ds_read_b128 v[28:31], v98 offset:44800
	v_add_f32_dpp v104, v104, v104 quad_perm:[2,3,0,1] row_mask:0xf bank_mask:0xf bound_ctrl:1
	v_pk_mul_f32 v[14:15], v[14:15], v[22:23] op_sel_hi:[1,0]
	v_pk_mul_f32 v[16:17], v[16:17], v[22:23] op_sel_hi:[1,0]
	v_add_f32_dpp v104, v104, v104 row_half_mirror row_mask:0xf bank_mask:0xf bound_ctrl:1
	s_waitcnt lgkmcnt(5)
	v_pk_fma_f32 v[14:15], v[100:101], v[6:7], v[14:15]
	v_pk_fma_f32 v[16:17], v[102:103], v[8:9], v[16:17]
	v_add_f32_dpp v104, v104, v104 row_mirror row_mask:0xf bank_mask:0xf bound_ctrl:1
	v_pk_fma_f32 v[100:101], v[10:11], v[104:105], v[14:15] op_sel_hi:[1,0,1] neg_lo:[0,1,0] neg_hi:[0,1,0]
	v_pk_fma_f32 v[102:103], v[12:13], v[104:105], v[16:17] op_sel_hi:[1,0,1] neg_lo:[0,1,0] neg_hi:[0,1,0]
	v_pk_mul_f32 v[106:107], v[100:101], v[18:19]
	ds_read_b128 v[32:35], v98 offset:45056
	v_pk_fma_f32 v[106:107], v[102:103], v[20:21], v[106:107]
	s_waitcnt lgkmcnt(2)
	v_pk_mul_f32 v[104:105], v[100:101], v[24:25]
	v_add_f32_e32 v106, v106, v107
	ds_read_b128 v[84:87], v98 offset:45568
	v_pk_fma_f32 v[104:105], v[102:103], v[26:27], v[104:105]
	v_add_f32_dpp v106, v106, v106 quad_perm:[1,0,3,2] row_mask:0xf bank_mask:0xf bound_ctrl:1
	v_add_f32_e32 v104, v104, v105
	ds_write_b32 v97, v106 offset:14336
	ds_read_b32 v22, v99 offset:47360
	ds_read_b128 v[14:17], v98 offset:46848
	v_add_f32_dpp v104, v104, v104 quad_perm:[1,0,3,2] row_mask:0xf bank_mask:0xf bound_ctrl:1
	ds_read_b128 v[2:5], v98 offset:46080
	ds_read_b128 v[6:9], v98 offset:46336
	v_add_f32_dpp v104, v104, v104 quad_perm:[2,3,0,1] row_mask:0xf bank_mask:0xf bound_ctrl:1
	v_pk_mul_f32 v[36:37], v[36:37], v[40:41] op_sel_hi:[1,0]
	v_pk_mul_f32 v[38:39], v[38:39], v[40:41] op_sel_hi:[1,0]
	v_add_f32_dpp v104, v104, v104 row_half_mirror row_mask:0xf bank_mask:0xf bound_ctrl:1
	s_waitcnt lgkmcnt(5)
	v_pk_fma_f32 v[36:37], v[100:101], v[28:29], v[36:37]
	v_pk_fma_f32 v[38:39], v[102:103], v[30:31], v[38:39]
	v_add_f32_dpp v104, v104, v104 row_mirror row_mask:0xf bank_mask:0xf bound_ctrl:1
	v_pk_fma_f32 v[100:101], v[32:33], v[104:105], v[36:37] op_sel_hi:[1,0,1] neg_lo:[0,1,0] neg_hi:[0,1,0]
	v_pk_fma_f32 v[102:103], v[34:35], v[104:105], v[38:39] op_sel_hi:[1,0,1] neg_lo:[0,1,0] neg_hi:[0,1,0]
	v_pk_mul_f32 v[106:107], v[100:101], v[84:85]
	ds_read_b128 v[10:13], v98 offset:46592
	v_pk_fma_f32 v[106:107], v[102:103], v[86:87], v[106:107]
	s_waitcnt lgkmcnt(2)
	v_pk_mul_f32 v[104:105], v[100:101], v[2:3]
	v_add_f32_e32 v106, v106, v107
	ds_read_b128 v[18:21], v98 offset:47104
	v_pk_fma_f32 v[104:105], v[102:103], v[4:5], v[104:105]
	v_add_f32_dpp v106, v106, v106 quad_perm:[1,0,3,2] row_mask:0xf bank_mask:0xf bound_ctrl:1
	v_add_f32_e32 v104, v104, v105
	ds_write_b32 v97, v106 offset:14848
	ds_read_b32 v40, v99 offset:48896
	ds_read_b128 v[36:39], v98 offset:48384
	v_add_f32_dpp v104, v104, v104 quad_perm:[1,0,3,2] row_mask:0xf bank_mask:0xf bound_ctrl:1
	ds_read_b128 v[24:27], v98 offset:47616
	ds_read_b128 v[28:31], v98 offset:47872
	v_add_f32_dpp v104, v104, v104 quad_perm:[2,3,0,1] row_mask:0xf bank_mask:0xf bound_ctrl:1
	v_pk_mul_f32 v[14:15], v[14:15], v[22:23] op_sel_hi:[1,0]
	v_pk_mul_f32 v[16:17], v[16:17], v[22:23] op_sel_hi:[1,0]
	v_add_f32_dpp v104, v104, v104 row_half_mirror row_mask:0xf bank_mask:0xf bound_ctrl:1
	s_waitcnt lgkmcnt(5)
	v_pk_fma_f32 v[14:15], v[100:101], v[6:7], v[14:15]
	v_pk_fma_f32 v[16:17], v[102:103], v[8:9], v[16:17]
	v_add_f32_dpp v104, v104, v104 row_mirror row_mask:0xf bank_mask:0xf bound_ctrl:1
	v_pk_fma_f32 v[100:101], v[10:11], v[104:105], v[14:15] op_sel_hi:[1,0,1] neg_lo:[0,1,0] neg_hi:[0,1,0]
	v_pk_fma_f32 v[102:103], v[12:13], v[104:105], v[16:17] op_sel_hi:[1,0,1] neg_lo:[0,1,0] neg_hi:[0,1,0]
	v_pk_mul_f32 v[106:107], v[100:101], v[18:19]
	ds_read_b128 v[32:35], v98 offset:48128
	v_pk_fma_f32 v[106:107], v[102:103], v[20:21], v[106:107]
	s_waitcnt lgkmcnt(2)
	v_pk_mul_f32 v[104:105], v[100:101], v[24:25]
	v_add_f32_e32 v106, v106, v107
	ds_read_b128 v[84:87], v98 offset:48640
	v_pk_fma_f32 v[104:105], v[102:103], v[26:27], v[104:105]
	v_add_f32_dpp v106, v106, v106 quad_perm:[1,0,3,2] row_mask:0xf bank_mask:0xf bound_ctrl:1
	v_add_f32_e32 v104, v104, v105
	ds_write_b32 v97, v106 offset:15360
	v_add_f32_dpp v104, v104, v104 quad_perm:[1,0,3,2] row_mask:0xf bank_mask:0xf bound_ctrl:1
	v_pk_mul_f32 v[36:37], v[36:37], v[40:41] op_sel_hi:[1,0]
	v_pk_mul_f32 v[38:39], v[38:39], v[40:41] op_sel_hi:[1,0]
	v_add_f32_dpp v104, v104, v104 quad_perm:[2,3,0,1] row_mask:0xf bank_mask:0xf bound_ctrl:1
	s_waitcnt lgkmcnt(1)
	v_pk_fma_f32 v[36:37], v[100:101], v[28:29], v[36:37]
	v_pk_fma_f32 v[38:39], v[102:103], v[30:31], v[38:39]
	v_add_f32_dpp v104, v104, v104 row_half_mirror row_mask:0xf bank_mask:0xf bound_ctrl:1
	s_nop 1
	v_add_f32_dpp v104, v104, v104 row_mirror row_mask:0xf bank_mask:0xf bound_ctrl:1
	v_pk_fma_f32 v[100:101], v[32:33], v[104:105], v[36:37] op_sel_hi:[1,0,1] neg_lo:[0,1,0] neg_hi:[0,1,0]
	v_pk_fma_f32 v[102:103], v[34:35], v[104:105], v[38:39] op_sel_hi:[1,0,1] neg_lo:[0,1,0] neg_hi:[0,1,0]
	v_pk_mul_f32 v[106:107], v[100:101], v[84:85]
	s_nop 0
	v_pk_fma_f32 v[106:107], v[102:103], v[86:87], v[106:107]
	s_nop 0
	v_add_f32_e32 v106, v106, v107
	s_nop 1
	v_add_f32_dpp v106, v106, v106 quad_perm:[1,0,3,2] row_mask:0xf bank_mask:0xf bound_ctrl:1
	ds_write_b32 v97, v106 offset:15872

; DEVI void rwkv_scan_item(const Params& p, const int item, char* smem) {
;     ...
;   auto store_y = [&](int c) {
;     const float* yb = ybuf + (c & 1) * 2048;
; #pragma unroll
;     for (int i = 0; i < 2; ++i) {
;       const int idx = ltid + 256 * i; const int st = idx >> 4, rw = idx & 15;
;       const float4 q = *(const float4*)(yb + st * 64 + rw * 4);
;       YR[(tok0 + (size_t)c * 32 + st) * 768 + h * 64 + rq * 16 + rw] = (q.x + q.y) + (q.z + q.w);
;     }
;   };
.LBB0_522:
	s_andn2_b64 vcc, exec, s[66:67]
	s_cbranch_vccnz .LBB0_513
	s_add_i32 s58, s78, -1
	s_lshl_b32 s66, s58, 13
	s_and_b32 s66, s66, 0x2000
	v_add_u32_e32 v6, s66, v83
	v_lshl_add_u32 v2, v88, 2, v6
	v_lshl_add_u32 v7, v89, 2, v6
	v_lshlrev_b32_e32 v2, 1, v2
	v_lshlrev_b32_e32 v7, 1, v7
	v_add_u32_e32 v2, 0xfffe7ff0, v2
	v_add_u32_e32 v7, 0xfffe7ff0, v7
	ds_read_b128 v[8:11], v2
	ds_read_b128 v[12:15], v2 offset:16
	ds_read_b128 v[16:19], v7
	ds_read_b128 v[20:23], v7 offset:16
	s_lshl_b32 s58, s58, 5
	s_add_u32 s66, s60, s58
	s_addc_u32 s67, s61, 0
	v_lshl_add_u64 v[2:3], s[66:67], 0, v[48:49]
	v_mad_u64_u32 v[4:5], s[82:83], v2, s72, v[66:67]
	v_mad_i32_i24 v5, v3, s72, v5
	v_lshl_add_u64 v[2:3], s[66:67], 0, v[46:47]
	v_mad_u64_u32 v[24:25], s[82:83], v2, s72, v[66:67]
	v_mad_i32_i24 v25, v3, s72, v25
	s_waitcnt lgkmcnt(0)
	v_add_f32_e32 v8, v8, v9
	v_add_f32_e32 v9, v10, v11
	v_add_f32_e32 v8, v8, v9
	v_add_f32_e32 v12, v12, v13
	v_add_f32_e32 v13, v14, v15
	v_add_f32_e32 v12, v12, v13
	v_add_f32_e32 v8, v8, v12
	v_add_f32_e32 v16, v16, v17
	v_add_f32_e32 v17, v18, v19
	v_add_f32_e32 v16, v16, v17
	v_add_f32_e32 v20, v20, v21
	v_add_f32_e32 v21, v22, v23
	v_add_f32_e32 v20, v20, v21
	v_add_f32_e32 v16, v16, v20
	global_store_dword v[4:5], v8, off
	global_store_dword v[24:25], v16, off
	s_branch .LBB0_513
.LBB0_524:
	s_and_saveexec_b64 s[62:63], s[0:1]
	s_cbranch_execz .LBB0_509
	v_lshlrev_b32_e32 v2, 1, v90
	v_lshlrev_b32_e32 v7, 1, v91
	v_add_u32_e32 v2, 0xfffe7ff0, v2
	v_add_u32_e32 v7, 0xfffe7ff0, v7
	ds_read_b128 v[8:11], v2
	ds_read_b128 v[12:15], v2 offset:16
	ds_read_b128 v[16:19], v7
	ds_read_b128 v[20:23], v7 offset:16
	s_or_b32 s60, s60, 0x3fe0
	v_lshl_add_u64 v[2:3], s[60:61], 0, v[48:49]
	v_mad_u64_u32 v[4:5], s[64:65], v2, s72, v[66:67]
	v_mad_i32_i24 v5, v3, s72, v5
	v_lshl_add_u64 v[2:3], s[60:61], 0, v[46:47]
	v_mad_u64_u32 v[24:25], s[64:65], v2, s72, v[66:67]
	v_mad_i32_i24 v25, v3, s72, v25
	s_waitcnt lgkmcnt(0)
	v_add_f32_e32 v8, v8, v9
	v_add_f32_e32 v9, v10, v11
	v_add_f32_e32 v8, v8, v9
	v_add_f32_e32 v12, v12, v13
	v_add_f32_e32 v13, v14, v15
	v_add_f32_e32 v12, v12, v13
	v_add_f32_e32 v8, v8, v12
	v_add_f32_e32 v16, v16, v17
	v_add_f32_e32 v17, v18, v19
	v_add_f32_e32 v16, v16, v17
	v_add_f32_e32 v20, v20, v21
	v_add_f32_e32 v21, v22, v23
	v_add_f32_e32 v20, v20, v21
	v_add_f32_e32 v16, v16, v20
	global_store_dword v[4:5], v8, off
	global_store_dword v[24:25], v16, off
	s_branch .LBB0_509

; DEVI void rwkv_scan_item(const Params& p, const int item, char* smem) {
;     ...
;       const float* sb = buf + (c & 1) * 12288 + kp * 4;
;       float* yb = ybuf + (c & 1) * 2048 + row16 * 4 + (kp >> 2);
;       const int vofs = 320 + rq * 16 + row16 - kp * 4;
.LBB0_1290:
	s_and_saveexec_b64 s[58:59], s[2:3]
	s_xor_b64 s[58:59], exec, s[58:59]
	s_cbranch_execz .LBB0_1295
	s_and_b32 s52, s65, 1
	s_mul_i32 s52, s52, 0xc000
	v_add_u32_e32 v98, s52, v83
	ds_read_b128 v[2:5], v98
	v_lshl_add_u32 v99, v63, 2, v98
	ds_read_b32 v22, v99 offset:1280
	ds_read_b128 v[14:17], v98 offset:768
	ds_read_b128 v[6:9], v98 offset:256
	ds_read_b128 v[10:13], v98 offset:512
	ds_read_b128 v[18:21], v98 offset:1024
	s_and_b32 s52, s65, 1
	s_lshl_b32 s52, s52, 14
	s_add_i32 s52, s52, 0x18010
	v_bfe_u32 v41, v0, 4, 4
	v_bfe_u32 v80, v0, 1, 3
	v_lshlrev_b32_e32 v41, 5, v41
	v_lshl_add_u32 v41, v80, 2, v41
	v_add_u32_e32 v97, s52, v41
	s_waitcnt lgkmcnt(0)
	v_pk_mul_f32 v[104:105], v[100:101], v[2:3]
	s_nop 0
	v_pk_fma_f32 v[104:105], v[102:103], v[4:5], v[104:105]
	s_nop 0
	v_add_f32_e32 v104, v104, v105
	ds_read_b32 v40, v99 offset:2816
	ds_read_b128 v[36:39], v98 offset:2304
	v_add_f32_dpp v104, v104, v104 quad_perm:[1,0,3,2] row_mask:0xf bank_mask:0xf bound_ctrl:1
	ds_read_b128 v[24:27], v98 offset:1536
	ds_read_b128 v[28:31], v98 offset:1792
	v_add_f32_dpp v104, v104, v104 quad_perm:[2,3,0,1] row_mask:0xf bank_mask:0xf bound_ctrl:1
	v_pk_mul_f32 v[14:15], v[14:15], v[22:23] op_sel_hi:[1,0]
	v_pk_mul_f32 v[16:17], v[16:17], v[22:23] op_sel_hi:[1,0]
	v_add_f32_dpp v104, v104, v104 row_half_mirror row_mask:0xf bank_mask:0xf bound_ctrl:1
	s_waitcnt lgkmcnt(5)
	v_pk_fma_f32 v[14:15], v[100:101], v[6:7], v[14:15]
	v_pk_fma_f32 v[16:17], v[102:103], v[8:9], v[16:17]
	v_add_f32_dpp v104, v104, v104 row_mirror row_mask:0xf bank_mask:0xf bound_ctrl:1
	v_pk_fma_f32 v[100:101], v[10:11], v[104:105], v[14:15] op_sel_hi:[1,0,1] neg_lo:[0,1,0] neg_hi:[0,1,0]
	v_pk_fma_f32 v[102:103], v[12:13], v[104:105], v[16:17] op_sel_hi:[1,0,1] neg_lo:[0,1,0] neg_hi:[0,1,0]
	v_pk_mul_f32 v[106:107], v[100:101], v[18:19]
	ds_read_b128 v[32:35], v98 offset:2048
	v_pk_fma_f32 v[106:107], v[102:103], v[20:21], v[106:107]
	s_waitcnt lgkmcnt(2)
	v_pk_mul_f32 v[104:105], v[100:101], v[24:25]
	v_add_f32_e32 v106, v106, v107
	ds_read_b128 v[84:87], v98 offset:2560
	v_pk_fma_f32 v[104:105], v[102:103], v[26:27], v[104:105]
	v_add_f32_dpp v106, v106, v106 quad_perm:[1,0,3,2] row_mask:0xf bank_mask:0xf bound_ctrl:1
	v_add_f32_e32 v104, v104, v105
	ds_write_b32 v97, v106 offset:0
	ds_read_b32 v22, v99 offset:4352
	ds_read_b128 v[14:17], v98 offset:3840
	v_add_f32_dpp v104, v104, v104 quad_perm:[1,0,3,2] row_mask:0xf bank_mask:0xf bound_ctrl:1
	ds_read_b128 v[2:5], v98 offset:3072
	ds_read_b128 v[6:9], v98 offset:3328
	v_add_f32_dpp v104, v104, v104 quad_perm:[2,3,0,1] row_mask:0xf bank_mask:0xf bound_ctrl:1
	v_pk_mul_f32 v[36:37], v[36:37], v[40:41] op_sel_hi:[1,0]
	v_pk_mul_f32 v[38:39], v[38:39], v[40:41] op_sel_hi:[1,0]
	v_add_f32_dpp v104, v104, v104 row_half_mirror row_mask:0xf bank_mask:0xf bound_ctrl:1
	s_waitcnt lgkmcnt(5)
	v_pk_fma_f32 v[36:37], v[100:101], v[28:29], v[36:37]
	v_pk_fma_f32 v[38:39], v[102:103], v[30:31], v[38:39]
	v_add_f32_dpp v104, v104, v104 row_mirror row_mask:0xf bank_mask:0xf bound_ctrl:1
	v_pk_fma_f32 v[100:101], v[32:33], v[104:105], v[36:37] op_sel_hi:[1,0,1] neg_lo:[0,1,0] neg_hi:[0,1,0]
	v_pk_fma_f32 v[102:103], v[34:35], v[104:105], v[38:39] op_sel_hi:[1,0,1] neg_lo:[0,1,0] neg_hi:[0,1,0]
	v_pk_mul_f32 v[106:107], v[100:101], v[84:85]
	ds_read_b128 v[10:13], v98 offset:3584
	v_pk_fma_f32 v[106:107], v[102:103], v[86:87], v[106:107]
	s_waitcnt lgkmcnt(2)
	v_pk_mul_f32 v[104:105], v[100:101], v[2:3]
	v_add_f32_e32 v106, v106, v107
	ds_read_b128 v[18:21], v98 offset:4096
	v_pk_fma_f32 v[104:105], v[102:103], v[4:5], v[104:105]
	v_add_f32_dpp v106, v106, v106 quad_perm:[1,0,3,2] row_mask:0xf bank_mask:0xf bound_ctrl:1
	v_add_f32_e32 v104, v104, v105
	ds_write_b32 v97, v106 offset:512
	ds_read_b32 v40, v99 offset:5888
	ds_read_b128 v[36:39], v98 offset:5376
	v_add_f32_dpp v104, v104, v104 quad_perm:[1,0,3,2] row_mask:0xf bank_mask:0xf bound_ctrl:1
	ds_read_b128 v[24:27], v98 offset:4608
	ds_read_b128 v[28:31], v98 offset:4864
	v_add_f32_dpp v104, v104, v104 quad_perm:[2,3,0,1] row_mask:0xf bank_mask:0xf bound_ctrl:1
	v_pk_mul_f32 v[14:15], v[14:15], v[22:23] op_sel_hi:[1,0]
	v_pk_mul_f32 v[16:17], v[16:17], v[22:23] op_sel_hi:[1,0]
	v_add_f32_dpp v104, v104, v104 row_half_mirror row_mask:0xf bank_mask:0xf bound_ctrl:1
	s_waitcnt lgkmcnt(5)
	v_pk_fma_f32 v[14:15], v[100:101], v[6:7], v[14:15]
	v_pk_fma_f32 v[16:17], v[102:103], v[8:9], v[16:17]
	v_add_f32_dpp v104, v104, v104 row_mirror row_mask:0xf bank_mask:0xf bound_ctrl:1
	v_pk_fma_f32 v[100:101], v[10:11], v[104:105], v[14:15] op_sel_hi:[1,0,1] neg_lo:[0,1,0] neg_hi:[0,1,0]
	v_pk_fma_f32 v[102:103], v[12:13], v[104:105], v[16:17] op_sel_hi:[1,0,1] neg_lo:[0,1,0] neg_hi:[0,1,0]
	v_pk_mul_f32 v[106:107], v[100:101], v[18:19]
	ds_read_b128 v[32:35], v98 offset:5120
	v_pk_fma_f32 v[106:107], v[102:103], v[20:21], v[106:107]
	s_waitcnt lgkmcnt(2)
	v_pk_mul_f32 v[104:105], v[100:101], v[24:25]
	v_add_f32_e32 v106, v106, v107
	ds_read_b128 v[84:87], v98 offset:5632
	v_pk_fma_f32 v[104:105], v[102:103], v[26:27], v[104:105]
	v_add_f32_dpp v106, v106, v106 quad_perm:[1,0,3,2] row_mask:0xf bank_mask:0xf bound_ctrl:1
	v_add_f32_e32 v104, v104, v105
	ds_write_b32 v97, v106 offset:1024
	ds_read_b32 v22, v99 offset:7424
	ds_read_b128 v[14:17], v98 offset:6912
	v_add_f32_dpp v104, v104, v104 quad_perm:[1,0,3,2] row_mask:0xf bank_mask:0xf bound_ctrl:1
	ds_read_b128 v[2:5], v98 offset:6144
	ds_read_b128 v[6:9], v98 offset:6400
	v_add_f32_dpp v104, v104, v104 quad_perm:[2,3,0,1] row_mask:0xf bank_mask:0xf bound_ctrl:1
	v_pk_mul_f32 v[36:37], v[36:37], v[40:41] op_sel_hi:[1,0]
	v_pk_mul_f32 v[38:39], v[38:39], v[40:41] op_sel_hi:[1,0]
	v_add_f32_dpp v104, v104, v104 row_half_mirror row_mask:0xf bank_mask:0xf bound_ctrl:1
	s_waitcnt lgkmcnt(5)
; DEVI void rwkv_scan_item(const Params& p, const int item, char* smem) {
;     ...
;   for (int c = 0; c < NC; ++c) {
;     if (wid >= 4) {
;       if (c + 1 < NC) load_chunk(c + 1, (c + 1) & 1);
;       if (c >= 1) store_y(c - 1);
;     } else {
;       const float* sb = buf + (c & 1) * 12288 + kp * 4;
;       float* yb = ybuf + (c & 1) * 2048 + row16 * 4 + (kp >> 2);
;       const int vofs = 320 + rq * 16 + row16 - kp * 4;
;       f32x4 kkA, wA, kaA, kA, rA, kkB, wB, kaB, kB, rB; float vA, vB;
;       RW_LD(0, A)
; #pragma unroll 2
;       for (int s = 0; s < 32; s += 2) {
;         RW_LD(s + 1, B)
;         __builtin_amdgcn_sched_barrier(0);
;         RW_STEP(s, A)
;         __builtin_amdgcn_sched_barrier(0);
;         if (s + 2 < 32) RW_LD(s + 2, A)
;         __builtin_amdgcn_sched_barrier(0);
;         RW_STEP(s + 1, B)
;         __builtin_amdgcn_sched_barrier(0);
;       }
	v_pk_fma_f32 v[36:37], v[100:101], v[28:29], v[36:37]
	v_pk_fma_f32 v[38:39], v[102:103], v[30:31], v[38:39]
	v_add_f32_dpp v104, v104, v104 row_mirror row_mask:0xf bank_mask:0xf bound_ctrl:1
	v_pk_fma_f32 v[100:101], v[32:33], v[104:105], v[36:37] op_sel_hi:[1,0,1] neg_lo:[0,1,0] neg_hi:[0,1,0]
	v_pk_fma_f32 v[102:103], v[34:35], v[104:105], v[38:39] op_sel_hi:[1,0,1] neg_lo:[0,1,0] neg_hi:[0,1,0]
	v_pk_mul_f32 v[106:107], v[100:101], v[84:85]
	ds_read_b128 v[10:13], v98 offset:6656
	v_pk_fma_f32 v[106:107], v[102:103], v[86:87], v[106:107]
	s_waitcnt lgkmcnt(2)
	v_pk_mul_f32 v[104:105], v[100:101], v[2:3]
	v_add_f32_e32 v106, v106, v107
	ds_read_b128 v[18:21], v98 offset:7168
	v_pk_fma_f32 v[104:105], v[102:103], v[4:5], v[104:105]
	v_add_f32_dpp v106, v106, v106 quad_perm:[1,0,3,2] row_mask:0xf bank_mask:0xf bound_ctrl:1
	v_add_f32_e32 v104, v104, v105
	ds_write_b32 v97, v106 offset:1536
	ds_read_b32 v40, v99 offset:8960
	ds_read_b128 v[36:39], v98 offset:8448
	v_add_f32_dpp v104, v104, v104 quad_perm:[1,0,3,2] row_mask:0xf bank_mask:0xf bound_ctrl:1
	ds_read_b128 v[24:27], v98 offset:7680
	ds_read_b128 v[28:31], v98 offset:7936
	v_add_f32_dpp v104, v104, v104 quad_perm:[2,3,0,1] row_mask:0xf bank_mask:0xf bound_ctrl:1
	v_pk_mul_f32 v[14:15], v[14:15], v[22:23] op_sel_hi:[1,0]
	v_pk_mul_f32 v[16:17], v[16:17], v[22:23] op_sel_hi:[1,0]
	v_add_f32_dpp v104, v104, v104 row_half_mirror row_mask:0xf bank_mask:0xf bound_ctrl:1
	s_waitcnt lgkmcnt(5)
	v_pk_fma_f32 v[14:15], v[100:101], v[6:7], v[14:15]
	v_pk_fma_f32 v[16:17], v[102:103], v[8:9], v[16:17]
	v_add_f32_dpp v104, v104, v104 row_mirror row_mask:0xf bank_mask:0xf bound_ctrl:1
	v_pk_fma_f32 v[100:101], v[10:11], v[104:105], v[14:15] op_sel_hi:[1,0,1] neg_lo:[0,1,0] neg_hi:[0,1,0]
	v_pk_fma_f32 v[102:103], v[12:13], v[104:105], v[16:17] op_sel_hi:[1,0,1] neg_lo:[0,1,0] neg_hi:[0,1,0]
	v_pk_mul_f32 v[106:107], v[100:101], v[18:19]
	ds_read_b128 v[32:35], v98 offset:8192
	v_pk_fma_f32 v[106:107], v[102:103], v[20:21], v[106:107]
	s_waitcnt lgkmcnt(2)
	v_pk_mul_f32 v[104:105], v[100:101], v[24:25]
	v_add_f32_e32 v106, v106, v107
	ds_read_b128 v[84:87], v98 offset:8704
	v_pk_fma_f32 v[104:105], v[102:103], v[26:27], v[104:105]
	v_add_f32_dpp v106, v106, v106 quad_perm:[1,0,3,2] row_mask:0xf bank_mask:0xf bound_ctrl:1
	v_add_f32_e32 v104, v104, v105
	ds_write_b32 v97, v106 offset:2048
	ds_read_b32 v22, v99 offset:10496
	ds_read_b128 v[14:17], v98 offset:9984
	v_add_f32_dpp v104, v104, v104 quad_perm:[1,0,3,2] row_mask:0xf bank_mask:0xf bound_ctrl:1
	ds_read_b128 v[2:5], v98 offset:9216
	ds_read_b128 v[6:9], v98 offset:9472
	v_add_f32_dpp v104, v104, v104 quad_perm:[2,3,0,1] row_mask:0xf bank_mask:0xf bound_ctrl:1
	v_pk_mul_f32 v[36:37], v[36:37], v[40:41] op_sel_hi:[1,0]
	v_pk_mul_f32 v[38:39], v[38:39], v[40:41] op_sel_hi:[1,0]
	v_add_f32_dpp v104, v104, v104 row_half_mirror row_mask:0xf bank_mask:0xf bound_ctrl:1
	s_waitcnt lgkmcnt(5)
	v_pk_fma_f32 v[36:37], v[100:101], v[28:29], v[36:37]
	v_pk_fma_f32 v[38:39], v[102:103], v[30:31], v[38:39]
	v_add_f32_dpp v104, v104, v104 row_mirror row_mask:0xf bank_mask:0xf bound_ctrl:1
	v_pk_fma_f32 v[100:101], v[32:33], v[104:105], v[36:37] op_sel_hi:[1,0,1] neg_lo:[0,1,0] neg_hi:[0,1,0]
	v_pk_fma_f32 v[102:103], v[34:35], v[104:105], v[38:39] op_sel_hi:[1,0,1] neg_lo:[0,1,0] neg_hi:[0,1,0]
	v_pk_mul_f32 v[106:107], v[100:101], v[84:85]
	ds_read_b128 v[10:13], v98 offset:9728
	v_pk_fma_f32 v[106:107], v[102:103], v[86:87], v[106:107]
	s_waitcnt lgkmcnt(2)
	v_pk_mul_f32 v[104:105], v[100:101], v[2:3]
	v_add_f32_e32 v106, v106, v107
	ds_read_b128 v[18:21], v98 offset:10240
	v_pk_fma_f32 v[104:105], v[102:103], v[4:5], v[104:105]
	v_add_f32_dpp v106, v106, v106 quad_perm:[1,0,3,2] row_mask:0xf bank_mask:0xf bound_ctrl:1
	v_add_f32_e32 v104, v104, v105
	ds_write_b32 v97, v106 offset:2560
	ds_read_b32 v40, v99 offset:12032
	ds_read_b128 v[36:39], v98 offset:11520
	v_add_f32_dpp v104, v104, v104 quad_perm:[1,0,3,2] row_mask:0xf bank_mask:0xf bound_ctrl:1
	ds_read_b128 v[24:27], v98 offset:10752
	ds_read_b128 v[28:31], v98 offset:11008
	v_add_f32_dpp v104, v104, v104 quad_perm:[2,3,0,1] row_mask:0xf bank_mask:0xf bound_ctrl:1
	v_pk_mul_f32 v[14:15], v[14:15], v[22:23] op_sel_hi:[1,0]
	v_pk_mul_f32 v[16:17], v[16:17], v[22:23] op_sel_hi:[1,0]
	v_add_f32_dpp v104, v104, v104 row_half_mirror row_mask:0xf bank_mask:0xf bound_ctrl:1
	s_waitcnt lgkmcnt(5)
	v_pk_fma_f32 v[14:15], v[100:101], v[6:7], v[14:15]
	v_pk_fma_f32 v[16:17], v[102:103], v[8:9], v[16:17]
	v_add_f32_dpp v104, v104, v104 row_mirror row_mask:0xf bank_mask:0xf bound_ctrl:1
	v_pk_fma_f32 v[100:101], v[10:11], v[104:105], v[14:15] op_sel_hi:[1,0,1] neg_lo:[0,1,0] neg_hi:[0,1,0]
	v_pk_fma_f32 v[102:103], v[12:13], v[104:105], v[16:17] op_sel_hi:[1,0,1] neg_lo:[0,1,0] neg_hi:[0,1,0]
	v_pk_mul_f32 v[106:107], v[100:101], v[18:19]
	ds_read_b128 v[32:35], v98 offset:11264
	v_pk_fma_f32 v[106:107], v[102:103], v[20:21], v[106:107]
	s_waitcnt lgkmcnt(2)
	v_pk_mul_f32 v[104:105], v[100:101], v[24:25]
	v_add_f32_e32 v106, v106, v107
	ds_read_b128 v[84:87], v98 offset:11776
	v_pk_fma_f32 v[104:105], v[102:103], v[26:27], v[104:105]
	v_add_f32_dpp v106, v106, v106 quad_perm:[1,0,3,2] row_mask:0xf bank_mask:0xf bound_ctrl:1
	v_add_f32_e32 v104, v104, v105
	ds_write_b32 v97, v106 offset:3072
	ds_read_b32 v22, v99 offset:13568
	ds_read_b128 v[14:17], v98 offset:13056
	v_add_f32_dpp v104, v104, v104 quad_perm:[1,0,3,2] row_mask:0xf bank_mask:0xf bound_ctrl:1
	ds_read_b128 v[2:5], v98 offset:12288
	ds_read_b128 v[6:9], v98 offset:12544
	v_add_f32_dpp v104, v104, v104 quad_perm:[2,3,0,1] row_mask:0xf bank_mask:0xf bound_ctrl:1
	v_pk_mul_f32 v[36:37], v[36:37], v[40:41] op_sel_hi:[1,0]
	v_pk_mul_f32 v[38:39], v[38:39], v[40:41] op_sel_hi:[1,0]
	v_add_f32_dpp v104, v104, v104 row_half_mirror row_mask:0xf bank_mask:0xf bound_ctrl:1
	s_waitcnt lgkmcnt(5)
; DEVI void rwkv_scan_item(const Params& p, const int item, char* smem) {
;     ...
;   for (int c = 0; c < NC; ++c) {
;     if (wid >= 4) {
;       if (c + 1 < NC) load_chunk(c + 1, (c + 1) & 1);
;       if (c >= 1) store_y(c - 1);
;     } else {
;       const float* sb = buf + (c & 1) * 12288 + kp * 4;
;       float* yb = ybuf + (c & 1) * 2048 + row16 * 4 + (kp >> 2);
;       const int vofs = 320 + rq * 16 + row16 - kp * 4;
;       f32x4 kkA, wA, kaA, kA, rA, kkB, wB, kaB, kB, rB; float vA, vB;
;       RW_LD(0, A)
; #pragma unroll 2
;       for (int s = 0; s < 32; s += 2) {
;         RW_LD(s + 1, B)
;         __builtin_amdgcn_sched_barrier(0);
;         RW_STEP(s, A)
;         __builtin_amdgcn_sched_barrier(0);
;         if (s + 2 < 32) RW_LD(s + 2, A)
;         __builtin_amdgcn_sched_barrier(0);
;         RW_STEP(s + 1, B)
;         __builtin_amdgcn_sched_barrier(0);
;       }
	v_pk_fma_f32 v[36:37], v[100:101], v[28:29], v[36:37]
	v_pk_fma_f32 v[38:39], v[102:103], v[30:31], v[38:39]
	v_add_f32_dpp v104, v104, v104 row_mirror row_mask:0xf bank_mask:0xf bound_ctrl:1
	v_pk_fma_f32 v[100:101], v[32:33], v[104:105], v[36:37] op_sel_hi:[1,0,1] neg_lo:[0,1,0] neg_hi:[0,1,0]
	v_pk_fma_f32 v[102:103], v[34:35], v[104:105], v[38:39] op_sel_hi:[1,0,1] neg_lo:[0,1,0] neg_hi:[0,1,0]
	v_pk_mul_f32 v[106:107], v[100:101], v[84:85]
	ds_read_b128 v[10:13], v98 offset:12800
	v_pk_fma_f32 v[106:107], v[102:103], v[86:87], v[106:107]
	s_waitcnt lgkmcnt(2)
	v_pk_mul_f32 v[104:105], v[100:101], v[2:3]
	v_add_f32_e32 v106, v106, v107
	ds_read_b128 v[18:21], v98 offset:13312
	v_pk_fma_f32 v[104:105], v[102:103], v[4:5], v[104:105]
	v_add_f32_dpp v106, v106, v106 quad_perm:[1,0,3,2] row_mask:0xf bank_mask:0xf bound_ctrl:1
	v_add_f32_e32 v104, v104, v105
	ds_write_b32 v97, v106 offset:3584
	ds_read_b32 v40, v99 offset:15104
	ds_read_b128 v[36:39], v98 offset:14592
	v_add_f32_dpp v104, v104, v104 quad_perm:[1,0,3,2] row_mask:0xf bank_mask:0xf bound_ctrl:1
	ds_read_b128 v[24:27], v98 offset:13824
	ds_read_b128 v[28:31], v98 offset:14080
	v_add_f32_dpp v104, v104, v104 quad_perm:[2,3,0,1] row_mask:0xf bank_mask:0xf bound_ctrl:1
	v_pk_mul_f32 v[14:15], v[14:15], v[22:23] op_sel_hi:[1,0]
	v_pk_mul_f32 v[16:17], v[16:17], v[22:23] op_sel_hi:[1,0]
	v_add_f32_dpp v104, v104, v104 row_half_mirror row_mask:0xf bank_mask:0xf bound_ctrl:1
	s_waitcnt lgkmcnt(5)
	v_pk_fma_f32 v[14:15], v[100:101], v[6:7], v[14:15]
	v_pk_fma_f32 v[16:17], v[102:103], v[8:9], v[16:17]
	v_add_f32_dpp v104, v104, v104 row_mirror row_mask:0xf bank_mask:0xf bound_ctrl:1
	v_pk_fma_f32 v[100:101], v[10:11], v[104:105], v[14:15] op_sel_hi:[1,0,1] neg_lo:[0,1,0] neg_hi:[0,1,0]
	v_pk_fma_f32 v[102:103], v[12:13], v[104:105], v[16:17] op_sel_hi:[1,0,1] neg_lo:[0,1,0] neg_hi:[0,1,0]
	v_pk_mul_f32 v[106:107], v[100:101], v[18:19]
	ds_read_b128 v[32:35], v98 offset:14336
	v_pk_fma_f32 v[106:107], v[102:103], v[20:21], v[106:107]
	s_waitcnt lgkmcnt(2)
	v_pk_mul_f32 v[104:105], v[100:101], v[24:25]
	v_add_f32_e32 v106, v106, v107
	ds_read_b128 v[84:87], v98 offset:14848
	v_pk_fma_f32 v[104:105], v[102:103], v[26:27], v[104:105]
	v_add_f32_dpp v106, v106, v106 quad_perm:[1,0,3,2] row_mask:0xf bank_mask:0xf bound_ctrl:1
	v_add_f32_e32 v104, v104, v105
	ds_write_b32 v97, v106 offset:4096
	ds_read_b32 v22, v99 offset:16640
	ds_read_b128 v[14:17], v98 offset:16128
	v_add_f32_dpp v104, v104, v104 quad_perm:[1,0,3,2] row_mask:0xf bank_mask:0xf bound_ctrl:1
	ds_read_b128 v[2:5], v98 offset:15360
	ds_read_b128 v[6:9], v98 offset:15616
	v_add_f32_dpp v104, v104, v104 quad_perm:[2,3,0,1] row_mask:0xf bank_mask:0xf bound_ctrl:1
	v_pk_mul_f32 v[36:37], v[36:37], v[40:41] op_sel_hi:[1,0]
	v_pk_mul_f32 v[38:39], v[38:39], v[40:41] op_sel_hi:[1,0]
	v_add_f32_dpp v104, v104, v104 row_half_mirror row_mask:0xf bank_mask:0xf bound_ctrl:1
	s_waitcnt lgkmcnt(5)
	v_pk_fma_f32 v[36:37], v[100:101], v[28:29], v[36:37]
	v_pk_fma_f32 v[38:39], v[102:103], v[30:31], v[38:39]
	v_add_f32_dpp v104, v104, v104 row_mirror row_mask:0xf bank_mask:0xf bound_ctrl:1
	v_pk_fma_f32 v[100:101], v[32:33], v[104:105], v[36:37] op_sel_hi:[1,0,1] neg_lo:[0,1,0] neg_hi:[0,1,0]
	v_pk_fma_f32 v[102:103], v[34:35], v[104:105], v[38:39] op_sel_hi:[1,0,1] neg_lo:[0,1,0] neg_hi:[0,1,0]
	v_pk_mul_f32 v[106:107], v[100:101], v[84:85]
	ds_read_b128 v[10:13], v98 offset:15872
	v_pk_fma_f32 v[106:107], v[102:103], v[86:87], v[106:107]
	s_waitcnt lgkmcnt(2)
	v_pk_mul_f32 v[104:105], v[100:101], v[2:3]
	v_add_f32_e32 v106, v106, v107
	ds_read_b128 v[18:21], v98 offset:16384
	v_pk_fma_f32 v[104:105], v[102:103], v[4:5], v[104:105]
	v_add_f32_dpp v106, v106, v106 quad_perm:[1,0,3,2] row_mask:0xf bank_mask:0xf bound_ctrl:1
	v_add_f32_e32 v104, v104, v105
	ds_write_b32 v97, v106 offset:4608
	ds_read_b32 v40, v99 offset:18176
	ds_read_b128 v[36:39], v98 offset:17664
	v_add_f32_dpp v104, v104, v104 quad_perm:[1,0,3,2] row_mask:0xf bank_mask:0xf bound_ctrl:1
	ds_read_b128 v[24:27], v98 offset:16896
	ds_read_b128 v[28:31], v98 offset:17152
	v_add_f32_dpp v104, v104, v104 quad_perm:[2,3,0,1] row_mask:0xf bank_mask:0xf bound_ctrl:1
	v_pk_mul_f32 v[14:15], v[14:15], v[22:23] op_sel_hi:[1,0]
	v_pk_mul_f32 v[16:17], v[16:17], v[22:23] op_sel_hi:[1,0]
	v_add_f32_dpp v104, v104, v104 row_half_mirror row_mask:0xf bank_mask:0xf bound_ctrl:1
	s_waitcnt lgkmcnt(5)
	v_pk_fma_f32 v[14:15], v[100:101], v[6:7], v[14:15]
	v_pk_fma_f32 v[16:17], v[102:103], v[8:9], v[16:17]
	v_add_f32_dpp v104, v104, v104 row_mirror row_mask:0xf bank_mask:0xf bound_ctrl:1
	v_pk_fma_f32 v[100:101], v[10:11], v[104:105], v[14:15] op_sel_hi:[1,0,1] neg_lo:[0,1,0] neg_hi:[0,1,0]
	v_pk_fma_f32 v[102:103], v[12:13], v[104:105], v[16:17] op_sel_hi:[1,0,1] neg_lo:[0,1,0] neg_hi:[0,1,0]
	v_pk_mul_f32 v[106:107], v[100:101], v[18:19]
	ds_read_b128 v[32:35], v98 offset:17408
	v_pk_fma_f32 v[106:107], v[102:103], v[20:21], v[106:107]
	s_waitcnt lgkmcnt(2)
	v_pk_mul_f32 v[104:105], v[100:101], v[24:25]
	v_add_f32_e32 v106, v106, v107
	ds_read_b128 v[84:87], v98 offset:17920
	v_pk_fma_f32 v[104:105], v[102:103], v[26:27], v[104:105]
	v_add_f32_dpp v106, v106, v106 quad_perm:[1,0,3,2] row_mask:0xf bank_mask:0xf bound_ctrl:1
	v_add_f32_e32 v104, v104, v105
	ds_write_b32 v97, v106 offset:5120
	ds_read_b32 v22, v99 offset:19712
	ds_read_b128 v[14:17], v98 offset:19200
	v_add_f32_dpp v104, v104, v104 quad_perm:[1,0,3,2] row_mask:0xf bank_mask:0xf bound_ctrl:1
	ds_read_b128 v[2:5], v98 offset:18432
	ds_read_b128 v[6:9], v98 offset:18688
	v_add_f32_dpp v104, v104, v104 quad_perm:[2,3,0,1] row_mask:0xf bank_mask:0xf bound_ctrl:1
	v_pk_mul_f32 v[36:37], v[36:37], v[40:41] op_sel_hi:[1,0]
	v_pk_mul_f32 v[38:39], v[38:39], v[40:41] op_sel_hi:[1,0]
	v_add_f32_dpp v104, v104, v104 row_half_mirror row_mask:0xf bank_mask:0xf bound_ctrl:1
	s_waitcnt lgkmcnt(5)
; DEVI void rwkv_scan_item(const Params& p, const int item, char* smem) {
;     ...
;   for (int c = 0; c < NC; ++c) {
;     if (wid >= 4) {
;       if (c + 1 < NC) load_chunk(c + 1, (c + 1) & 1);
;       if (c >= 1) store_y(c - 1);
;     } else {
;       const float* sb = buf + (c & 1) * 12288 + kp * 4;
;       float* yb = ybuf + (c & 1) * 2048 + row16 * 4 + (kp >> 2);
;       const int vofs = 320 + rq * 16 + row16 - kp * 4;
;       f32x4 kkA, wA, kaA, kA, rA, kkB, wB, kaB, kB, rB; float vA, vB;
;       RW_LD(0, A)
; #pragma unroll 2
;       for (int s = 0; s < 32; s += 2) {
;         RW_LD(s + 1, B)
;         __builtin_amdgcn_sched_barrier(0);
;         RW_STEP(s, A)
;         __builtin_amdgcn_sched_barrier(0);
;         if (s + 2 < 32) RW_LD(s + 2, A)
;         __builtin_amdgcn_sched_barrier(0);
;         RW_STEP(s + 1, B)
;         __builtin_amdgcn_sched_barrier(0);
;       }
	v_pk_fma_f32 v[36:37], v[100:101], v[28:29], v[36:37]
	v_pk_fma_f32 v[38:39], v[102:103], v[30:31], v[38:39]
	v_add_f32_dpp v104, v104, v104 row_mirror row_mask:0xf bank_mask:0xf bound_ctrl:1
	v_pk_fma_f32 v[100:101], v[32:33], v[104:105], v[36:37] op_sel_hi:[1,0,1] neg_lo:[0,1,0] neg_hi:[0,1,0]
	v_pk_fma_f32 v[102:103], v[34:35], v[104:105], v[38:39] op_sel_hi:[1,0,1] neg_lo:[0,1,0] neg_hi:[0,1,0]
	v_pk_mul_f32 v[106:107], v[100:101], v[84:85]
	ds_read_b128 v[10:13], v98 offset:18944
	v_pk_fma_f32 v[106:107], v[102:103], v[86:87], v[106:107]
	s_waitcnt lgkmcnt(2)
	v_pk_mul_f32 v[104:105], v[100:101], v[2:3]
	v_add_f32_e32 v106, v106, v107
	ds_read_b128 v[18:21], v98 offset:19456
	v_pk_fma_f32 v[104:105], v[102:103], v[4:5], v[104:105]
	v_add_f32_dpp v106, v106, v106 quad_perm:[1,0,3,2] row_mask:0xf bank_mask:0xf bound_ctrl:1
	v_add_f32_e32 v104, v104, v105
	ds_write_b32 v97, v106 offset:5632
	ds_read_b32 v40, v99 offset:21248
	ds_read_b128 v[36:39], v98 offset:20736
	v_add_f32_dpp v104, v104, v104 quad_perm:[1,0,3,2] row_mask:0xf bank_mask:0xf bound_ctrl:1
	ds_read_b128 v[24:27], v98 offset:19968
	ds_read_b128 v[28:31], v98 offset:20224
	v_add_f32_dpp v104, v104, v104 quad_perm:[2,3,0,1] row_mask:0xf bank_mask:0xf bound_ctrl:1
	v_pk_mul_f32 v[14:15], v[14:15], v[22:23] op_sel_hi:[1,0]
	v_pk_mul_f32 v[16:17], v[16:17], v[22:23] op_sel_hi:[1,0]
	v_add_f32_dpp v104, v104, v104 row_half_mirror row_mask:0xf bank_mask:0xf bound_ctrl:1
	s_waitcnt lgkmcnt(5)
	v_pk_fma_f32 v[14:15], v[100:101], v[6:7], v[14:15]
	v_pk_fma_f32 v[16:17], v[102:103], v[8:9], v[16:17]
	v_add_f32_dpp v104, v104, v104 row_mirror row_mask:0xf bank_mask:0xf bound_ctrl:1
	v_pk_fma_f32 v[100:101], v[10:11], v[104:105], v[14:15] op_sel_hi:[1,0,1] neg_lo:[0,1,0] neg_hi:[0,1,0]
	v_pk_fma_f32 v[102:103], v[12:13], v[104:105], v[16:17] op_sel_hi:[1,0,1] neg_lo:[0,1,0] neg_hi:[0,1,0]
	v_pk_mul_f32 v[106:107], v[100:101], v[18:19]
	ds_read_b128 v[32:35], v98 offset:20480
	v_pk_fma_f32 v[106:107], v[102:103], v[20:21], v[106:107]
	s_waitcnt lgkmcnt(2)
	v_pk_mul_f32 v[104:105], v[100:101], v[24:25]
	v_add_f32_e32 v106, v106, v107
	ds_read_b128 v[84:87], v98 offset:20992
	v_pk_fma_f32 v[104:105], v[102:103], v[26:27], v[104:105]
	v_add_f32_dpp v106, v106, v106 quad_perm:[1,0,3,2] row_mask:0xf bank_mask:0xf bound_ctrl:1
	v_add_f32_e32 v104, v104, v105
	ds_write_b32 v97, v106 offset:6144
	ds_read_b32 v22, v99 offset:22784
	ds_read_b128 v[14:17], v98 offset:22272
	v_add_f32_dpp v104, v104, v104 quad_perm:[1,0,3,2] row_mask:0xf bank_mask:0xf bound_ctrl:1
	ds_read_b128 v[2:5], v98 offset:21504
	ds_read_b128 v[6:9], v98 offset:21760
	v_add_f32_dpp v104, v104, v104 quad_perm:[2,3,0,1] row_mask:0xf bank_mask:0xf bound_ctrl:1
	v_pk_mul_f32 v[36:37], v[36:37], v[40:41] op_sel_hi:[1,0]
	v_pk_mul_f32 v[38:39], v[38:39], v[40:41] op_sel_hi:[1,0]
	v_add_f32_dpp v104, v104, v104 row_half_mirror row_mask:0xf bank_mask:0xf bound_ctrl:1
	s_waitcnt lgkmcnt(5)
	v_pk_fma_f32 v[36:37], v[100:101], v[28:29], v[36:37]
	v_pk_fma_f32 v[38:39], v[102:103], v[30:31], v[38:39]
	v_add_f32_dpp v104, v104, v104 row_mirror row_mask:0xf bank_mask:0xf bound_ctrl:1
	v_pk_fma_f32 v[100:101], v[32:33], v[104:105], v[36:37] op_sel_hi:[1,0,1] neg_lo:[0,1,0] neg_hi:[0,1,0]
	v_pk_fma_f32 v[102:103], v[34:35], v[104:105], v[38:39] op_sel_hi:[1,0,1] neg_lo:[0,1,0] neg_hi:[0,1,0]
	v_pk_mul_f32 v[106:107], v[100:101], v[84:85]
	ds_read_b128 v[10:13], v98 offset:22016
	v_pk_fma_f32 v[106:107], v[102:103], v[86:87], v[106:107]
	s_waitcnt lgkmcnt(2)
	v_pk_mul_f32 v[104:105], v[100:101], v[2:3]
	v_add_f32_e32 v106, v106, v107
	ds_read_b128 v[18:21], v98 offset:22528
	v_pk_fma_f32 v[104:105], v[102:103], v[4:5], v[104:105]
	v_add_f32_dpp v106, v106, v106 quad_perm:[1,0,3,2] row_mask:0xf bank_mask:0xf bound_ctrl:1
	v_add_f32_e32 v104, v104, v105
	ds_write_b32 v97, v106 offset:6656
	ds_read_b32 v40, v99 offset:24320
	ds_read_b128 v[36:39], v98 offset:23808
	v_add_f32_dpp v104, v104, v104 quad_perm:[1,0,3,2] row_mask:0xf bank_mask:0xf bound_ctrl:1
	ds_read_b128 v[24:27], v98 offset:23040
	ds_read_b128 v[28:31], v98 offset:23296
	v_add_f32_dpp v104, v104, v104 quad_perm:[2,3,0,1] row_mask:0xf bank_mask:0xf bound_ctrl:1
	v_pk_mul_f32 v[14:15], v[14:15], v[22:23] op_sel_hi:[1,0]
	v_pk_mul_f32 v[16:17], v[16:17], v[22:23] op_sel_hi:[1,0]
	v_add_f32_dpp v104, v104, v104 row_half_mirror row_mask:0xf bank_mask:0xf bound_ctrl:1
	s_waitcnt lgkmcnt(5)
	v_pk_fma_f32 v[14:15], v[100:101], v[6:7], v[14:15]
	v_pk_fma_f32 v[16:17], v[102:103], v[8:9], v[16:17]
	v_add_f32_dpp v104, v104, v104 row_mirror row_mask:0xf bank_mask:0xf bound_ctrl:1
	v_pk_fma_f32 v[100:101], v[10:11], v[104:105], v[14:15] op_sel_hi:[1,0,1] neg_lo:[0,1,0] neg_hi:[0,1,0]
	v_pk_fma_f32 v[102:103], v[12:13], v[104:105], v[16:17] op_sel_hi:[1,0,1] neg_lo:[0,1,0] neg_hi:[0,1,0]
	v_pk_mul_f32 v[106:107], v[100:101], v[18:19]
	ds_read_b128 v[32:35], v98 offset:23552
	v_pk_fma_f32 v[106:107], v[102:103], v[20:21], v[106:107]
	s_waitcnt lgkmcnt(2)
	v_pk_mul_f32 v[104:105], v[100:101], v[24:25]
	v_add_f32_e32 v106, v106, v107
	ds_read_b128 v[84:87], v98 offset:24064
	v_pk_fma_f32 v[104:105], v[102:103], v[26:27], v[104:105]
	v_add_f32_dpp v106, v106, v106 quad_perm:[1,0,3,2] row_mask:0xf bank_mask:0xf bound_ctrl:1
	v_add_f32_e32 v104, v104, v105
	ds_write_b32 v97, v106 offset:7168
	ds_read_b32 v22, v99 offset:25856
	ds_read_b128 v[14:17], v98 offset:25344
	v_add_f32_dpp v104, v104, v104 quad_perm:[1,0,3,2] row_mask:0xf bank_mask:0xf bound_ctrl:1
	ds_read_b128 v[2:5], v98 offset:24576
	ds_read_b128 v[6:9], v98 offset:24832
	v_add_f32_dpp v104, v104, v104 quad_perm:[2,3,0,1] row_mask:0xf bank_mask:0xf bound_ctrl:1
	v_pk_mul_f32 v[36:37], v[36:37], v[40:41] op_sel_hi:[1,0]
	v_pk_mul_f32 v[38:39], v[38:39], v[40:41] op_sel_hi:[1,0]
	v_add_f32_dpp v104, v104, v104 row_half_mirror row_mask:0xf bank_mask:0xf bound_ctrl:1
	s_waitcnt lgkmcnt(5)
; DEVI void rwkv_scan_item(const Params& p, const int item, char* smem) {
;     ...
;   for (int c = 0; c < NC; ++c) {
;     if (wid >= 4) {
;       if (c + 1 < NC) load_chunk(c + 1, (c + 1) & 1);
;       if (c >= 1) store_y(c - 1);
;     } else {
;       const float* sb = buf + (c & 1) * 12288 + kp * 4;
;       float* yb = ybuf + (c & 1) * 2048 + row16 * 4 + (kp >> 2);
;       const int vofs = 320 + rq * 16 + row16 - kp * 4;
;       f32x4 kkA, wA, kaA, kA, rA, kkB, wB, kaB, kB, rB; float vA, vB;
;       RW_LD(0, A)
; #pragma unroll 2
;       for (int s = 0; s < 32; s += 2) {
;         RW_LD(s + 1, B)
;         __builtin_amdgcn_sched_barrier(0);
;         RW_STEP(s, A)
;         __builtin_amdgcn_sched_barrier(0);
;         if (s + 2 < 32) RW_LD(s + 2, A)
;         __builtin_amdgcn_sched_barrier(0);
;         RW_STEP(s + 1, B)
;         __builtin_amdgcn_sched_barrier(0);
;       }
	v_pk_fma_f32 v[36:37], v[100:101], v[28:29], v[36:37]
	v_pk_fma_f32 v[38:39], v[102:103], v[30:31], v[38:39]
	v_add_f32_dpp v104, v104, v104 row_mirror row_mask:0xf bank_mask:0xf bound_ctrl:1
	v_pk_fma_f32 v[100:101], v[32:33], v[104:105], v[36:37] op_sel_hi:[1,0,1] neg_lo:[0,1,0] neg_hi:[0,1,0]
	v_pk_fma_f32 v[102:103], v[34:35], v[104:105], v[38:39] op_sel_hi:[1,0,1] neg_lo:[0,1,0] neg_hi:[0,1,0]
	v_pk_mul_f32 v[106:107], v[100:101], v[84:85]
	ds_read_b128 v[10:13], v98 offset:25088
	v_pk_fma_f32 v[106:107], v[102:103], v[86:87], v[106:107]
	s_waitcnt lgkmcnt(2)
	v_pk_mul_f32 v[104:105], v[100:101], v[2:3]
	v_add_f32_e32 v106, v106, v107
	ds_read_b128 v[18:21], v98 offset:25600
	v_pk_fma_f32 v[104:105], v[102:103], v[4:5], v[104:105]
	v_add_f32_dpp v106, v106, v106 quad_perm:[1,0,3,2] row_mask:0xf bank_mask:0xf bound_ctrl:1
	v_add_f32_e32 v104, v104, v105
	ds_write_b32 v97, v106 offset:7680
	ds_read_b32 v40, v99 offset:27392
	ds_read_b128 v[36:39], v98 offset:26880
	v_add_f32_dpp v104, v104, v104 quad_perm:[1,0,3,2] row_mask:0xf bank_mask:0xf bound_ctrl:1
	ds_read_b128 v[24:27], v98 offset:26112
	ds_read_b128 v[28:31], v98 offset:26368
	v_add_f32_dpp v104, v104, v104 quad_perm:[2,3,0,1] row_mask:0xf bank_mask:0xf bound_ctrl:1
	v_pk_mul_f32 v[14:15], v[14:15], v[22:23] op_sel_hi:[1,0]
	v_pk_mul_f32 v[16:17], v[16:17], v[22:23] op_sel_hi:[1,0]
	v_add_f32_dpp v104, v104, v104 row_half_mirror row_mask:0xf bank_mask:0xf bound_ctrl:1
	s_waitcnt lgkmcnt(5)
	v_pk_fma_f32 v[14:15], v[100:101], v[6:7], v[14:15]
	v_pk_fma_f32 v[16:17], v[102:103], v[8:9], v[16:17]
	v_add_f32_dpp v104, v104, v104 row_mirror row_mask:0xf bank_mask:0xf bound_ctrl:1
	v_pk_fma_f32 v[100:101], v[10:11], v[104:105], v[14:15] op_sel_hi:[1,0,1] neg_lo:[0,1,0] neg_hi:[0,1,0]
	v_pk_fma_f32 v[102:103], v[12:13], v[104:105], v[16:17] op_sel_hi:[1,0,1] neg_lo:[0,1,0] neg_hi:[0,1,0]
	v_pk_mul_f32 v[106:107], v[100:101], v[18:19]
	ds_read_b128 v[32:35], v98 offset:26624
	v_pk_fma_f32 v[106:107], v[102:103], v[20:21], v[106:107]
	s_waitcnt lgkmcnt(2)
	v_pk_mul_f32 v[104:105], v[100:101], v[24:25]
	v_add_f32_e32 v106, v106, v107
	ds_read_b128 v[84:87], v98 offset:27136
	v_pk_fma_f32 v[104:105], v[102:103], v[26:27], v[104:105]
	v_add_f32_dpp v106, v106, v106 quad_perm:[1,0,3,2] row_mask:0xf bank_mask:0xf bound_ctrl:1
	v_add_f32_e32 v104, v104, v105
	ds_write_b32 v97, v106 offset:8192
	ds_read_b32 v22, v99 offset:28928
	ds_read_b128 v[14:17], v98 offset:28416
	v_add_f32_dpp v104, v104, v104 quad_perm:[1,0,3,2] row_mask:0xf bank_mask:0xf bound_ctrl:1
	ds_read_b128 v[2:5], v98 offset:27648
	ds_read_b128 v[6:9], v98 offset:27904
	v_add_f32_dpp v104, v104, v104 quad_perm:[2,3,0,1] row_mask:0xf bank_mask:0xf bound_ctrl:1
	v_pk_mul_f32 v[36:37], v[36:37], v[40:41] op_sel_hi:[1,0]
	v_pk_mul_f32 v[38:39], v[38:39], v[40:41] op_sel_hi:[1,0]
	v_add_f32_dpp v104, v104, v104 row_half_mirror row_mask:0xf bank_mask:0xf bound_ctrl:1
	s_waitcnt lgkmcnt(5)
	v_pk_fma_f32 v[36:37], v[100:101], v[28:29], v[36:37]
	v_pk_fma_f32 v[38:39], v[102:103], v[30:31], v[38:39]
	v_add_f32_dpp v104, v104, v104 row_mirror row_mask:0xf bank_mask:0xf bound_ctrl:1
	v_pk_fma_f32 v[100:101], v[32:33], v[104:105], v[36:37] op_sel_hi:[1,0,1] neg_lo:[0,1,0] neg_hi:[0,1,0]
	v_pk_fma_f32 v[102:103], v[34:35], v[104:105], v[38:39] op_sel_hi:[1,0,1] neg_lo:[0,1,0] neg_hi:[0,1,0]
	v_pk_mul_f32 v[106:107], v[100:101], v[84:85]
	ds_read_b128 v[10:13], v98 offset:28160
	v_pk_fma_f32 v[106:107], v[102:103], v[86:87], v[106:107]
	s_waitcnt lgkmcnt(2)
	v_pk_mul_f32 v[104:105], v[100:101], v[2:3]
	v_add_f32_e32 v106, v106, v107
	ds_read_b128 v[18:21], v98 offset:28672
	v_pk_fma_f32 v[104:105], v[102:103], v[4:5], v[104:105]
	v_add_f32_dpp v106, v106, v106 quad_perm:[1,0,3,2] row_mask:0xf bank_mask:0xf bound_ctrl:1
	v_add_f32_e32 v104, v104, v105
	ds_write_b32 v97, v106 offset:8704
	ds_read_b32 v40, v99 offset:30464
	ds_read_b128 v[36:39], v98 offset:29952
	v_add_f32_dpp v104, v104, v104 quad_perm:[1,0,3,2] row_mask:0xf bank_mask:0xf bound_ctrl:1
	ds_read_b128 v[24:27], v98 offset:29184
	ds_read_b128 v[28:31], v98 offset:29440
	v_add_f32_dpp v104, v104, v104 quad_perm:[2,3,0,1] row_mask:0xf bank_mask:0xf bound_ctrl:1
	v_pk_mul_f32 v[14:15], v[14:15], v[22:23] op_sel_hi:[1,0]
	v_pk_mul_f32 v[16:17], v[16:17], v[22:23] op_sel_hi:[1,0]
	v_add_f32_dpp v104, v104, v104 row_half_mirror row_mask:0xf bank_mask:0xf bound_ctrl:1
	s_waitcnt lgkmcnt(5)
	v_pk_fma_f32 v[14:15], v[100:101], v[6:7], v[14:15]
	v_pk_fma_f32 v[16:17], v[102:103], v[8:9], v[16:17]
	v_add_f32_dpp v104, v104, v104 row_mirror row_mask:0xf bank_mask:0xf bound_ctrl:1
	v_pk_fma_f32 v[100:101], v[10:11], v[104:105], v[14:15] op_sel_hi:[1,0,1] neg_lo:[0,1,0] neg_hi:[0,1,0]
	v_pk_fma_f32 v[102:103], v[12:13], v[104:105], v[16:17] op_sel_hi:[1,0,1] neg_lo:[0,1,0] neg_hi:[0,1,0]
	v_pk_mul_f32 v[106:107], v[100:101], v[18:19]
	ds_read_b128 v[32:35], v98 offset:29696
	v_pk_fma_f32 v[106:107], v[102:103], v[20:21], v[106:107]
	s_waitcnt lgkmcnt(2)
	v_pk_mul_f32 v[104:105], v[100:101], v[24:25]
	v_add_f32_e32 v106, v106, v107
	ds_read_b128 v[84:87], v98 offset:30208
	v_pk_fma_f32 v[104:105], v[102:103], v[26:27], v[104:105]
	v_add_f32_dpp v106, v106, v106 quad_perm:[1,0,3,2] row_mask:0xf bank_mask:0xf bound_ctrl:1
	v_add_f32_e32 v104, v104, v105
	ds_write_b32 v97, v106 offset:9216
	ds_read_b32 v22, v99 offset:32000
	ds_read_b128 v[14:17], v98 offset:31488
	v_add_f32_dpp v104, v104, v104 quad_perm:[1,0,3,2] row_mask:0xf bank_mask:0xf bound_ctrl:1
	ds_read_b128 v[2:5], v98 offset:30720
	ds_read_b128 v[6:9], v98 offset:30976
	v_add_f32_dpp v104, v104, v104 quad_perm:[2,3,0,1] row_mask:0xf bank_mask:0xf bound_ctrl:1
	v_pk_mul_f32 v[36:37], v[36:37], v[40:41] op_sel_hi:[1,0]
	v_pk_mul_f32 v[38:39], v[38:39], v[40:41] op_sel_hi:[1,0]
	v_add_f32_dpp v104, v104, v104 row_half_mirror row_mask:0xf bank_mask:0xf bound_ctrl:1
	s_waitcnt lgkmcnt(5)
; DEVI void rwkv_scan_item(const Params& p, const int item, char* smem) {
;     ...
;   for (int c = 0; c < NC; ++c) {
;     if (wid >= 4) {
;       if (c + 1 < NC) load_chunk(c + 1, (c + 1) & 1);
;       if (c >= 1) store_y(c - 1);
;     } else {
;       const float* sb = buf + (c & 1) * 12288 + kp * 4;
;       float* yb = ybuf + (c & 1) * 2048 + row16 * 4 + (kp >> 2);
;       const int vofs = 320 + rq * 16 + row16 - kp * 4;
;       f32x4 kkA, wA, kaA, kA, rA, kkB, wB, kaB, kB, rB; float vA, vB;
;       RW_LD(0, A)
; #pragma unroll 2
;       for (int s = 0; s < 32; s += 2) {
;         RW_LD(s + 1, B)
;         __builtin_amdgcn_sched_barrier(0);
;         RW_STEP(s, A)
;         __builtin_amdgcn_sched_barrier(0);
;         if (s + 2 < 32) RW_LD(s + 2, A)
;         __builtin_amdgcn_sched_barrier(0);
;         RW_STEP(s + 1, B)
;         __builtin_amdgcn_sched_barrier(0);
;       }
	v_pk_fma_f32 v[36:37], v[100:101], v[28:29], v[36:37]
	v_pk_fma_f32 v[38:39], v[102:103], v[30:31], v[38:39]
	v_add_f32_dpp v104, v104, v104 row_mirror row_mask:0xf bank_mask:0xf bound_ctrl:1
	v_pk_fma_f32 v[100:101], v[32:33], v[104:105], v[36:37] op_sel_hi:[1,0,1] neg_lo:[0,1,0] neg_hi:[0,1,0]
	v_pk_fma_f32 v[102:103], v[34:35], v[104:105], v[38:39] op_sel_hi:[1,0,1] neg_lo:[0,1,0] neg_hi:[0,1,0]
	v_pk_mul_f32 v[106:107], v[100:101], v[84:85]
	ds_read_b128 v[10:13], v98 offset:31232
	v_pk_fma_f32 v[106:107], v[102:103], v[86:87], v[106:107]
	s_waitcnt lgkmcnt(2)
	v_pk_mul_f32 v[104:105], v[100:101], v[2:3]
	v_add_f32_e32 v106, v106, v107
	ds_read_b128 v[18:21], v98 offset:31744
	v_pk_fma_f32 v[104:105], v[102:103], v[4:5], v[104:105]
	v_add_f32_dpp v106, v106, v106 quad_perm:[1,0,3,2] row_mask:0xf bank_mask:0xf bound_ctrl:1
	v_add_f32_e32 v104, v104, v105
	ds_write_b32 v97, v106 offset:9728
	ds_read_b32 v40, v99 offset:33536
	ds_read_b128 v[36:39], v98 offset:33024
	v_add_f32_dpp v104, v104, v104 quad_perm:[1,0,3,2] row_mask:0xf bank_mask:0xf bound_ctrl:1
	ds_read_b128 v[24:27], v98 offset:32256
	ds_read_b128 v[28:31], v98 offset:32512
	v_add_f32_dpp v104, v104, v104 quad_perm:[2,3,0,1] row_mask:0xf bank_mask:0xf bound_ctrl:1
	v_pk_mul_f32 v[14:15], v[14:15], v[22:23] op_sel_hi:[1,0]
	v_pk_mul_f32 v[16:17], v[16:17], v[22:23] op_sel_hi:[1,0]
	v_add_f32_dpp v104, v104, v104 row_half_mirror row_mask:0xf bank_mask:0xf bound_ctrl:1
	s_waitcnt lgkmcnt(5)
	v_pk_fma_f32 v[14:15], v[100:101], v[6:7], v[14:15]
	v_pk_fma_f32 v[16:17], v[102:103], v[8:9], v[16:17]
	v_add_f32_dpp v104, v104, v104 row_mirror row_mask:0xf bank_mask:0xf bound_ctrl:1
	v_pk_fma_f32 v[100:101], v[10:11], v[104:105], v[14:15] op_sel_hi:[1,0,1] neg_lo:[0,1,0] neg_hi:[0,1,0]
	v_pk_fma_f32 v[102:103], v[12:13], v[104:105], v[16:17] op_sel_hi:[1,0,1] neg_lo:[0,1,0] neg_hi:[0,1,0]
	v_pk_mul_f32 v[106:107], v[100:101], v[18:19]
	ds_read_b128 v[32:35], v98 offset:32768
	v_pk_fma_f32 v[106:107], v[102:103], v[20:21], v[106:107]
	s_waitcnt lgkmcnt(2)
	v_pk_mul_f32 v[104:105], v[100:101], v[24:25]
	v_add_f32_e32 v106, v106, v107
	ds_read_b128 v[84:87], v98 offset:33280
	v_pk_fma_f32 v[104:105], v[102:103], v[26:27], v[104:105]
	v_add_f32_dpp v106, v106, v106 quad_perm:[1,0,3,2] row_mask:0xf bank_mask:0xf bound_ctrl:1
	v_add_f32_e32 v104, v104, v105
	ds_write_b32 v97, v106 offset:10240
	ds_read_b32 v22, v99 offset:35072
	ds_read_b128 v[14:17], v98 offset:34560
	v_add_f32_dpp v104, v104, v104 quad_perm:[1,0,3,2] row_mask:0xf bank_mask:0xf bound_ctrl:1
	ds_read_b128 v[2:5], v98 offset:33792
	ds_read_b128 v[6:9], v98 offset:34048
	v_add_f32_dpp v104, v104, v104 quad_perm:[2,3,0,1] row_mask:0xf bank_mask:0xf bound_ctrl:1
	v_pk_mul_f32 v[36:37], v[36:37], v[40:41] op_sel_hi:[1,0]
	v_pk_mul_f32 v[38:39], v[38:39], v[40:41] op_sel_hi:[1,0]
	v_add_f32_dpp v104, v104, v104 row_half_mirror row_mask:0xf bank_mask:0xf bound_ctrl:1
	s_waitcnt lgkmcnt(5)
	v_pk_fma_f32 v[36:37], v[100:101], v[28:29], v[36:37]
	v_pk_fma_f32 v[38:39], v[102:103], v[30:31], v[38:39]
	v_add_f32_dpp v104, v104, v104 row_mirror row_mask:0xf bank_mask:0xf bound_ctrl:1
	v_pk_fma_f32 v[100:101], v[32:33], v[104:105], v[36:37] op_sel_hi:[1,0,1] neg_lo:[0,1,0] neg_hi:[0,1,0]
	v_pk_fma_f32 v[102:103], v[34:35], v[104:105], v[38:39] op_sel_hi:[1,0,1] neg_lo:[0,1,0] neg_hi:[0,1,0]
	v_pk_mul_f32 v[106:107], v[100:101], v[84:85]
	ds_read_b128 v[10:13], v98 offset:34304
	v_pk_fma_f32 v[106:107], v[102:103], v[86:87], v[106:107]
	s_waitcnt lgkmcnt(2)
	v_pk_mul_f32 v[104:105], v[100:101], v[2:3]
	v_add_f32_e32 v106, v106, v107
	ds_read_b128 v[18:21], v98 offset:34816
	v_pk_fma_f32 v[104:105], v[102:103], v[4:5], v[104:105]
	v_add_f32_dpp v106, v106, v106 quad_perm:[1,0,3,2] row_mask:0xf bank_mask:0xf bound_ctrl:1
	v_add_f32_e32 v104, v104, v105
	ds_write_b32 v97, v106 offset:10752
	ds_read_b32 v40, v99 offset:36608
	ds_read_b128 v[36:39], v98 offset:36096
	v_add_f32_dpp v104, v104, v104 quad_perm:[1,0,3,2] row_mask:0xf bank_mask:0xf bound_ctrl:1
	ds_read_b128 v[24:27], v98 offset:35328
	ds_read_b128 v[28:31], v98 offset:35584
	v_add_f32_dpp v104, v104, v104 quad_perm:[2,3,0,1] row_mask:0xf bank_mask:0xf bound_ctrl:1
	v_pk_mul_f32 v[14:15], v[14:15], v[22:23] op_sel_hi:[1,0]
	v_pk_mul_f32 v[16:17], v[16:17], v[22:23] op_sel_hi:[1,0]
	v_add_f32_dpp v104, v104, v104 row_half_mirror row_mask:0xf bank_mask:0xf bound_ctrl:1
	s_waitcnt lgkmcnt(5)
	v_pk_fma_f32 v[14:15], v[100:101], v[6:7], v[14:15]
	v_pk_fma_f32 v[16:17], v[102:103], v[8:9], v[16:17]
	v_add_f32_dpp v104, v104, v104 row_mirror row_mask:0xf bank_mask:0xf bound_ctrl:1
	v_pk_fma_f32 v[100:101], v[10:11], v[104:105], v[14:15] op_sel_hi:[1,0,1] neg_lo:[0,1,0] neg_hi:[0,1,0]
	v_pk_fma_f32 v[102:103], v[12:13], v[104:105], v[16:17] op_sel_hi:[1,0,1] neg_lo:[0,1,0] neg_hi:[0,1,0]
	v_pk_mul_f32 v[106:107], v[100:101], v[18:19]
	ds_read_b128 v[32:35], v98 offset:35840
	v_pk_fma_f32 v[106:107], v[102:103], v[20:21], v[106:107]
	s_waitcnt lgkmcnt(2)
	v_pk_mul_f32 v[104:105], v[100:101], v[24:25]
	v_add_f32_e32 v106, v106, v107
	ds_read_b128 v[84:87], v98 offset:36352
	v_pk_fma_f32 v[104:105], v[102:103], v[26:27], v[104:105]
	v_add_f32_dpp v106, v106, v106 quad_perm:[1,0,3,2] row_mask:0xf bank_mask:0xf bound_ctrl:1
	v_add_f32_e32 v104, v104, v105
	ds_write_b32 v97, v106 offset:11264
	ds_read_b32 v22, v99 offset:38144
	ds_read_b128 v[14:17], v98 offset:37632
	v_add_f32_dpp v104, v104, v104 quad_perm:[1,0,3,2] row_mask:0xf bank_mask:0xf bound_ctrl:1
	ds_read_b128 v[2:5], v98 offset:36864
	ds_read_b128 v[6:9], v98 offset:37120
	v_add_f32_dpp v104, v104, v104 quad_perm:[2,3,0,1] row_mask:0xf bank_mask:0xf bound_ctrl:1
	v_pk_mul_f32 v[36:37], v[36:37], v[40:41] op_sel_hi:[1,0]
	v_pk_mul_f32 v[38:39], v[38:39], v[40:41] op_sel_hi:[1,0]
	v_add_f32_dpp v104, v104, v104 row_half_mirror row_mask:0xf bank_mask:0xf bound_ctrl:1
	s_waitcnt lgkmcnt(5)
; DEVI void rwkv_scan_item(const Params& p, const int item, char* smem) {
;     ...
;   for (int c = 0; c < NC; ++c) {
;     if (wid >= 4) {
;       if (c + 1 < NC) load_chunk(c + 1, (c + 1) & 1);
;       if (c >= 1) store_y(c - 1);
;     } else {
;       const float* sb = buf + (c & 1) * 12288 + kp * 4;
;       float* yb = ybuf + (c & 1) * 2048 + row16 * 4 + (kp >> 2);
;       const int vofs = 320 + rq * 16 + row16 - kp * 4;
;       f32x4 kkA, wA, kaA, kA, rA, kkB, wB, kaB, kB, rB; float vA, vB;
;       RW_LD(0, A)
; #pragma unroll 2
;       for (int s = 0; s < 32; s += 2) {
;         RW_LD(s + 1, B)
;         __builtin_amdgcn_sched_barrier(0);
;         RW_STEP(s, A)
;         __builtin_amdgcn_sched_barrier(0);
;         if (s + 2 < 32) RW_LD(s + 2, A)
;         __builtin_amdgcn_sched_barrier(0);
;         RW_STEP(s + 1, B)
;         __builtin_amdgcn_sched_barrier(0);
;       }
	v_pk_fma_f32 v[36:37], v[100:101], v[28:29], v[36:37]
	v_pk_fma_f32 v[38:39], v[102:103], v[30:31], v[38:39]
	v_add_f32_dpp v104, v104, v104 row_mirror row_mask:0xf bank_mask:0xf bound_ctrl:1
	v_pk_fma_f32 v[100:101], v[32:33], v[104:105], v[36:37] op_sel_hi:[1,0,1] neg_lo:[0,1,0] neg_hi:[0,1,0]
	v_pk_fma_f32 v[102:103], v[34:35], v[104:105], v[38:39] op_sel_hi:[1,0,1] neg_lo:[0,1,0] neg_hi:[0,1,0]
	v_pk_mul_f32 v[106:107], v[100:101], v[84:85]
	ds_read_b128 v[10:13], v98 offset:37376
	v_pk_fma_f32 v[106:107], v[102:103], v[86:87], v[106:107]
	s_waitcnt lgkmcnt(2)
	v_pk_mul_f32 v[104:105], v[100:101], v[2:3]
	v_add_f32_e32 v106, v106, v107
	ds_read_b128 v[18:21], v98 offset:37888
	v_pk_fma_f32 v[104:105], v[102:103], v[4:5], v[104:105]
	v_add_f32_dpp v106, v106, v106 quad_perm:[1,0,3,2] row_mask:0xf bank_mask:0xf bound_ctrl:1
	v_add_f32_e32 v104, v104, v105
	ds_write_b32 v97, v106 offset:11776
	ds_read_b32 v40, v99 offset:39680
	ds_read_b128 v[36:39], v98 offset:39168
	v_add_f32_dpp v104, v104, v104 quad_perm:[1,0,3,2] row_mask:0xf bank_mask:0xf bound_ctrl:1
	ds_read_b128 v[24:27], v98 offset:38400
	ds_read_b128 v[28:31], v98 offset:38656
	v_add_f32_dpp v104, v104, v104 quad_perm:[2,3,0,1] row_mask:0xf bank_mask:0xf bound_ctrl:1
	v_pk_mul_f32 v[14:15], v[14:15], v[22:23] op_sel_hi:[1,0]
	v_pk_mul_f32 v[16:17], v[16:17], v[22:23] op_sel_hi:[1,0]
	v_add_f32_dpp v104, v104, v104 row_half_mirror row_mask:0xf bank_mask:0xf bound_ctrl:1
	s_waitcnt lgkmcnt(5)
	v_pk_fma_f32 v[14:15], v[100:101], v[6:7], v[14:15]
	v_pk_fma_f32 v[16:17], v[102:103], v[8:9], v[16:17]
	v_add_f32_dpp v104, v104, v104 row_mirror row_mask:0xf bank_mask:0xf bound_ctrl:1
	v_pk_fma_f32 v[100:101], v[10:11], v[104:105], v[14:15] op_sel_hi:[1,0,1] neg_lo:[0,1,0] neg_hi:[0,1,0]
	v_pk_fma_f32 v[102:103], v[12:13], v[104:105], v[16:17] op_sel_hi:[1,0,1] neg_lo:[0,1,0] neg_hi:[0,1,0]
	v_pk_mul_f32 v[106:107], v[100:101], v[18:19]
	ds_read_b128 v[32:35], v98 offset:38912
	v_pk_fma_f32 v[106:107], v[102:103], v[20:21], v[106:107]
	s_waitcnt lgkmcnt(2)
	v_pk_mul_f32 v[104:105], v[100:101], v[24:25]
	v_add_f32_e32 v106, v106, v107
	ds_read_b128 v[84:87], v98 offset:39424
	v_pk_fma_f32 v[104:105], v[102:103], v[26:27], v[104:105]
	v_add_f32_dpp v106, v106, v106 quad_perm:[1,0,3,2] row_mask:0xf bank_mask:0xf bound_ctrl:1
	v_add_f32_e32 v104, v104, v105
	ds_write_b32 v97, v106 offset:12288
	ds_read_b32 v22, v99 offset:41216
	ds_read_b128 v[14:17], v98 offset:40704
	v_add_f32_dpp v104, v104, v104 quad_perm:[1,0,3,2] row_mask:0xf bank_mask:0xf bound_ctrl:1
	ds_read_b128 v[2:5], v98 offset:39936
	ds_read_b128 v[6:9], v98 offset:40192
	v_add_f32_dpp v104, v104, v104 quad_perm:[2,3,0,1] row_mask:0xf bank_mask:0xf bound_ctrl:1
	v_pk_mul_f32 v[36:37], v[36:37], v[40:41] op_sel_hi:[1,0]
	v_pk_mul_f32 v[38:39], v[38:39], v[40:41] op_sel_hi:[1,0]
	v_add_f32_dpp v104, v104, v104 row_half_mirror row_mask:0xf bank_mask:0xf bound_ctrl:1
	s_waitcnt lgkmcnt(5)
	v_pk_fma_f32 v[36:37], v[100:101], v[28:29], v[36:37]
	v_pk_fma_f32 v[38:39], v[102:103], v[30:31], v[38:39]
	v_add_f32_dpp v104, v104, v104 row_mirror row_mask:0xf bank_mask:0xf bound_ctrl:1
	v_pk_fma_f32 v[100:101], v[32:33], v[104:105], v[36:37] op_sel_hi:[1,0,1] neg_lo:[0,1,0] neg_hi:[0,1,0]
	v_pk_fma_f32 v[102:103], v[34:35], v[104:105], v[38:39] op_sel_hi:[1,0,1] neg_lo:[0,1,0] neg_hi:[0,1,0]
	v_pk_mul_f32 v[106:107], v[100:101], v[84:85]
	ds_read_b128 v[10:13], v98 offset:40448
	v_pk_fma_f32 v[106:107], v[102:103], v[86:87], v[106:107]
	s_waitcnt lgkmcnt(2)
	v_pk_mul_f32 v[104:105], v[100:101], v[2:3]
	v_add_f32_e32 v106, v106, v107
	ds_read_b128 v[18:21], v98 offset:40960
	v_pk_fma_f32 v[104:105], v[102:103], v[4:5], v[104:105]
	v_add_f32_dpp v106, v106, v106 quad_perm:[1,0,3,2] row_mask:0xf bank_mask:0xf bound_ctrl:1
	v_add_f32_e32 v104, v104, v105
	ds_write_b32 v97, v106 offset:12800
	ds_read_b32 v40, v99 offset:42752
	ds_read_b128 v[36:39], v98 offset:42240
	v_add_f32_dpp v104, v104, v104 quad_perm:[1,0,3,2] row_mask:0xf bank_mask:0xf bound_ctrl:1
	ds_read_b128 v[24:27], v98 offset:41472
	ds_read_b128 v[28:31], v98 offset:41728
	v_add_f32_dpp v104, v104, v104 quad_perm:[2,3,0,1] row_mask:0xf bank_mask:0xf bound_ctrl:1
	v_pk_mul_f32 v[14:15], v[14:15], v[22:23] op_sel_hi:[1,0]
	v_pk_mul_f32 v[16:17], v[16:17], v[22:23] op_sel_hi:[1,0]
	v_add_f32_dpp v104, v104, v104 row_half_mirror row_mask:0xf bank_mask:0xf bound_ctrl:1
	s_waitcnt lgkmcnt(5)
	v_pk_fma_f32 v[14:15], v[100:101], v[6:7], v[14:15]
	v_pk_fma_f32 v[16:17], v[102:103], v[8:9], v[16:17]
	v_add_f32_dpp v104, v104, v104 row_mirror row_mask:0xf bank_mask:0xf bound_ctrl:1
	v_pk_fma_f32 v[100:101], v[10:11], v[104:105], v[14:15] op_sel_hi:[1,0,1] neg_lo:[0,1,0] neg_hi:[0,1,0]
	v_pk_fma_f32 v[102:103], v[12:13], v[104:105], v[16:17] op_sel_hi:[1,0,1] neg_lo:[0,1,0] neg_hi:[0,1,0]
	v_pk_mul_f32 v[106:107], v[100:101], v[18:19]
	ds_read_b128 v[32:35], v98 offset:41984
	v_pk_fma_f32 v[106:107], v[102:103], v[20:21], v[106:107]
	s_waitcnt lgkmcnt(2)
	v_pk_mul_f32 v[104:105], v[100:101], v[24:25]
	v_add_f32_e32 v106, v106, v107
	ds_read_b128 v[84:87], v98 offset:42496
	v_pk_fma_f32 v[104:105], v[102:103], v[26:27], v[104:105]
	v_add_f32_dpp v106, v106, v106 quad_perm:[1,0,3,2] row_mask:0xf bank_mask:0xf bound_ctrl:1
	v_add_f32_e32 v104, v104, v105
	ds_write_b32 v97, v106 offset:13312
	ds_read_b32 v22, v99 offset:44288
	ds_read_b128 v[14:17], v98 offset:43776
	v_add_f32_dpp v104, v104, v104 quad_perm:[1,0,3,2] row_mask:0xf bank_mask:0xf bound_ctrl:1
	ds_read_b128 v[2:5], v98 offset:43008
	ds_read_b128 v[6:9], v98 offset:43264
	v_add_f32_dpp v104, v104, v104 quad_perm:[2,3,0,1] row_mask:0xf bank_mask:0xf bound_ctrl:1
	v_pk_mul_f32 v[36:37], v[36:37], v[40:41] op_sel_hi:[1,0]
	v_pk_mul_f32 v[38:39], v[38:39], v[40:41] op_sel_hi:[1,0]
	v_add_f32_dpp v104, v104, v104 row_half_mirror row_mask:0xf bank_mask:0xf bound_ctrl:1
	s_waitcnt lgkmcnt(5)
; DEVI void rwkv_scan_item(const Params& p, const int item, char* smem) {
;     ...
;   for (int c = 0; c < NC; ++c) {
;     if (wid >= 4) {
;       if (c + 1 < NC) load_chunk(c + 1, (c + 1) & 1);
;       if (c >= 1) store_y(c - 1);
;     } else {
;       const float* sb = buf + (c & 1) * 12288 + kp * 4;
;       float* yb = ybuf + (c & 1) * 2048 + row16 * 4 + (kp >> 2);
;       const int vofs = 320 + rq * 16 + row16 - kp * 4;
;       f32x4 kkA, wA, kaA, kA, rA, kkB, wB, kaB, kB, rB; float vA, vB;
;       RW_LD(0, A)
; #pragma unroll 2
;       for (int s = 0; s < 32; s += 2) {
;         RW_LD(s + 1, B)
;         __builtin_amdgcn_sched_barrier(0);
;         RW_STEP(s, A)
;         __builtin_amdgcn_sched_barrier(0);
;         if (s + 2 < 32) RW_LD(s + 2, A)
;         __builtin_amdgcn_sched_barrier(0);
;         RW_STEP(s + 1, B)
;         __builtin_amdgcn_sched_barrier(0);
;       }
	v_pk_fma_f32 v[36:37], v[100:101], v[28:29], v[36:37]
	v_pk_fma_f32 v[38:39], v[102:103], v[30:31], v[38:39]
	v_add_f32_dpp v104, v104, v104 row_mirror row_mask:0xf bank_mask:0xf bound_ctrl:1
	v_pk_fma_f32 v[100:101], v[32:33], v[104:105], v[36:37] op_sel_hi:[1,0,1] neg_lo:[0,1,0] neg_hi:[0,1,0]
	v_pk_fma_f32 v[102:103], v[34:35], v[104:105], v[38:39] op_sel_hi:[1,0,1] neg_lo:[0,1,0] neg_hi:[0,1,0]
	v_pk_mul_f32 v[106:107], v[100:101], v[84:85]
	ds_read_b128 v[10:13], v98 offset:43520
	v_pk_fma_f32 v[106:107], v[102:103], v[86:87], v[106:107]
	s_waitcnt lgkmcnt(2)
	v_pk_mul_f32 v[104:105], v[100:101], v[2:3]
	v_add_f32_e32 v106, v106, v107
	ds_read_b128 v[18:21], v98 offset:44032
	v_pk_fma_f32 v[104:105], v[102:103], v[4:5], v[104:105]
	v_add_f32_dpp v106, v106, v106 quad_perm:[1,0,3,2] row_mask:0xf bank_mask:0xf bound_ctrl:1
	v_add_f32_e32 v104, v104, v105
	ds_write_b32 v97, v106 offset:13824
	ds_read_b32 v40, v99 offset:45824
	ds_read_b128 v[36:39], v98 offset:45312
	v_add_f32_dpp v104, v104, v104 quad_perm:[1,0,3,2] row_mask:0xf bank_mask:0xf bound_ctrl:1
	ds_read_b128 v[24:27], v98 offset:44544
	ds_read_b128 v[28:31], v98 offset:44800
	v_add_f32_dpp v104, v104, v104 quad_perm:[2,3,0,1] row_mask:0xf bank_mask:0xf bound_ctrl:1
	v_pk_mul_f32 v[14:15], v[14:15], v[22:23] op_sel_hi:[1,0]
	v_pk_mul_f32 v[16:17], v[16:17], v[22:23] op_sel_hi:[1,0]
	v_add_f32_dpp v104, v104, v104 row_half_mirror row_mask:0xf bank_mask:0xf bound_ctrl:1
	s_waitcnt lgkmcnt(5)
	v_pk_fma_f32 v[14:15], v[100:101], v[6:7], v[14:15]
	v_pk_fma_f32 v[16:17], v[102:103], v[8:9], v[16:17]
	v_add_f32_dpp v104, v104, v104 row_mirror row_mask:0xf bank_mask:0xf bound_ctrl:1
	v_pk_fma_f32 v[100:101], v[10:11], v[104:105], v[14:15] op_sel_hi:[1,0,1] neg_lo:[0,1,0] neg_hi:[0,1,0]
	v_pk_fma_f32 v[102:103], v[12:13], v[104:105], v[16:17] op_sel_hi:[1,0,1] neg_lo:[0,1,0] neg_hi:[0,1,0]
	v_pk_mul_f32 v[106:107], v[100:101], v[18:19]
	ds_read_b128 v[32:35], v98 offset:45056
	v_pk_fma_f32 v[106:107], v[102:103], v[20:21], v[106:107]
	s_waitcnt lgkmcnt(2)
	v_pk_mul_f32 v[104:105], v[100:101], v[24:25]
	v_add_f32_e32 v106, v106, v107
	ds_read_b128 v[84:87], v98 offset:45568
	v_pk_fma_f32 v[104:105], v[102:103], v[26:27], v[104:105]
	v_add_f32_dpp v106, v106, v106 quad_perm:[1,0,3,2] row_mask:0xf bank_mask:0xf bound_ctrl:1
	v_add_f32_e32 v104, v104, v105
	ds_write_b32 v97, v106 offset:14336
	ds_read_b32 v22, v99 offset:47360
	ds_read_b128 v[14:17], v98 offset:46848
	v_add_f32_dpp v104, v104, v104 quad_perm:[1,0,3,2] row_mask:0xf bank_mask:0xf bound_ctrl:1
	ds_read_b128 v[2:5], v98 offset:46080
	ds_read_b128 v[6:9], v98 offset:46336
	v_add_f32_dpp v104, v104, v104 quad_perm:[2,3,0,1] row_mask:0xf bank_mask:0xf bound_ctrl:1
	v_pk_mul_f32 v[36:37], v[36:37], v[40:41] op_sel_hi:[1,0]
	v_pk_mul_f32 v[38:39], v[38:39], v[40:41] op_sel_hi:[1,0]
	v_add_f32_dpp v104, v104, v104 row_half_mirror row_mask:0xf bank_mask:0xf bound_ctrl:1
	s_waitcnt lgkmcnt(5)
	v_pk_fma_f32 v[36:37], v[100:101], v[28:29], v[36:37]
	v_pk_fma_f32 v[38:39], v[102:103], v[30:31], v[38:39]
	v_add_f32_dpp v104, v104, v104 row_mirror row_mask:0xf bank_mask:0xf bound_ctrl:1
	v_pk_fma_f32 v[100:101], v[32:33], v[104:105], v[36:37] op_sel_hi:[1,0,1] neg_lo:[0,1,0] neg_hi:[0,1,0]
	v_pk_fma_f32 v[102:103], v[34:35], v[104:105], v[38:39] op_sel_hi:[1,0,1] neg_lo:[0,1,0] neg_hi:[0,1,0]
	v_pk_mul_f32 v[106:107], v[100:101], v[84:85]
	ds_read_b128 v[10:13], v98 offset:46592
	v_pk_fma_f32 v[106:107], v[102:103], v[86:87], v[106:107]
	s_waitcnt lgkmcnt(2)
	v_pk_mul_f32 v[104:105], v[100:101], v[2:3]
	v_add_f32_e32 v106, v106, v107
	ds_read_b128 v[18:21], v98 offset:47104
	v_pk_fma_f32 v[104:105], v[102:103], v[4:5], v[104:105]
	v_add_f32_dpp v106, v106, v106 quad_perm:[1,0,3,2] row_mask:0xf bank_mask:0xf bound_ctrl:1
	v_add_f32_e32 v104, v104, v105
	ds_write_b32 v97, v106 offset:14848
	ds_read_b32 v40, v99 offset:48896
	ds_read_b128 v[36:39], v98 offset:48384
	v_add_f32_dpp v104, v104, v104 quad_perm:[1,0,3,2] row_mask:0xf bank_mask:0xf bound_ctrl:1
	ds_read_b128 v[24:27], v98 offset:47616
	ds_read_b128 v[28:31], v98 offset:47872
	v_add_f32_dpp v104, v104, v104 quad_perm:[2,3,0,1] row_mask:0xf bank_mask:0xf bound_ctrl:1
	v_pk_mul_f32 v[14:15], v[14:15], v[22:23] op_sel_hi:[1,0]
	v_pk_mul_f32 v[16:17], v[16:17], v[22:23] op_sel_hi:[1,0]
	v_add_f32_dpp v104, v104, v104 row_half_mirror row_mask:0xf bank_mask:0xf bound_ctrl:1
	s_waitcnt lgkmcnt(5)
	v_pk_fma_f32 v[14:15], v[100:101], v[6:7], v[14:15]
	v_pk_fma_f32 v[16:17], v[102:103], v[8:9], v[16:17]
	v_add_f32_dpp v104, v104, v104 row_mirror row_mask:0xf bank_mask:0xf bound_ctrl:1
	v_pk_fma_f32 v[100:101], v[10:11], v[104:105], v[14:15] op_sel_hi:[1,0,1] neg_lo:[0,1,0] neg_hi:[0,1,0]
	v_pk_fma_f32 v[102:103], v[12:13], v[104:105], v[16:17] op_sel_hi:[1,0,1] neg_lo:[0,1,0] neg_hi:[0,1,0]
	v_pk_mul_f32 v[106:107], v[100:101], v[18:19]
	ds_read_b128 v[32:35], v98 offset:48128
	v_pk_fma_f32 v[106:107], v[102:103], v[20:21], v[106:107]
	s_waitcnt lgkmcnt(2)
	v_pk_mul_f32 v[104:105], v[100:101], v[24:25]
	v_add_f32_e32 v106, v106, v107
	ds_read_b128 v[84:87], v98 offset:48640
	v_pk_fma_f32 v[104:105], v[102:103], v[26:27], v[104:105]
	v_add_f32_dpp v106, v106, v106 quad_perm:[1,0,3,2] row_mask:0xf bank_mask:0xf bound_ctrl:1
	v_add_f32_e32 v104, v104, v105
	ds_write_b32 v97, v106 offset:15360
	v_add_f32_dpp v104, v104, v104 quad_perm:[1,0,3,2] row_mask:0xf bank_mask:0xf bound_ctrl:1
	v_pk_mul_f32 v[36:37], v[36:37], v[40:41] op_sel_hi:[1,0]
	v_pk_mul_f32 v[38:39], v[38:39], v[40:41] op_sel_hi:[1,0]
	v_add_f32_dpp v104, v104, v104 quad_perm:[2,3,0,1] row_mask:0xf bank_mask:0xf bound_ctrl:1
	s_waitcnt lgkmcnt(1)
	v_pk_fma_f32 v[36:37], v[100:101], v[28:29], v[36:37]
	v_pk_fma_f32 v[38:39], v[102:103], v[30:31], v[38:39]
	v_add_f32_dpp v104, v104, v104 row_half_mirror row_mask:0xf bank_mask:0xf bound_ctrl:1
	s_nop 1
	v_add_f32_dpp v104, v104, v104 row_mirror row_mask:0xf bank_mask:0xf bound_ctrl:1
	v_pk_fma_f32 v[100:101], v[32:33], v[104:105], v[36:37] op_sel_hi:[1,0,1] neg_lo:[0,1,0] neg_hi:[0,1,0]
	v_pk_fma_f32 v[102:103], v[34:35], v[104:105], v[38:39] op_sel_hi:[1,0,1] neg_lo:[0,1,0] neg_hi:[0,1,0]
	v_pk_mul_f32 v[106:107], v[100:101], v[84:85]
	s_nop 0
	v_pk_fma_f32 v[106:107], v[102:103], v[86:87], v[106:107]
	s_nop 0
	v_add_f32_e32 v106, v106, v107
	s_nop 1
	v_add_f32_dpp v106, v106, v106 quad_perm:[1,0,3,2] row_mask:0xf bank_mask:0xf bound_ctrl:1
	ds_write_b32 v97, v106 offset:15872

; DEVI void rwkv_scan_item(const Params& p, const int item, char* smem) {
;     ...
;   auto store_y = [&](int c) {
;     const float* yb = ybuf + (c & 1) * 2048;
; #pragma unroll
;     for (int i = 0; i < 2; ++i) {
;       const int idx = ltid + 256 * i; const int st = idx >> 4, rw = idx & 15;
;       const float4 q = *(const float4*)(yb + st * 64 + rw * 4);
;       YR[(tok0 + (size_t)c * 32 + st) * 768 + h * 64 + rq * 16 + rw] = (q.x + q.y) + (q.z + q.w);
;     }
;   };
.LBB0_1298:
	s_andn2_b64 vcc, exec, s[60:61]
	s_cbranch_vccnz .LBB0_1289
	s_add_i32 s52, s65, -1
	s_lshl_b32 s60, s52, 13
	s_and_b32 s60, s60, 0x2000
	v_add_u32_e32 v6, s60, v88
	v_lshl_add_u32 v2, v89, 2, v6
	v_lshl_add_u32 v7, v90, 2, v6
	v_lshlrev_b32_e32 v2, 1, v2
	v_lshlrev_b32_e32 v7, 1, v7
	v_add_u32_e32 v2, 0xfffe7ff0, v2
	v_add_u32_e32 v7, 0xfffe7ff0, v7
	ds_read_b128 v[8:11], v2
	ds_read_b128 v[12:15], v2 offset:16
	ds_read_b128 v[16:19], v7
	ds_read_b128 v[20:23], v7 offset:16
	s_lshl_b32 s52, s52, 5
	s_add_u32 s60, s54, s52
	s_addc_u32 s61, s55, 0
	v_lshl_add_u64 v[2:3], s[60:61], 0, v[48:49]
	v_mad_u64_u32 v[4:5], s[66:67], v2, s63, v[66:67]
	v_mad_i32_i24 v5, v3, s63, v5
	v_lshl_add_u64 v[2:3], s[60:61], 0, v[42:43]
	v_mad_u64_u32 v[24:25], s[66:67], v2, s63, v[66:67]
	v_mad_i32_i24 v25, v3, s63, v25
	s_waitcnt lgkmcnt(0)
	v_add_f32_e32 v8, v8, v9
	v_add_f32_e32 v9, v10, v11
	v_add_f32_e32 v8, v8, v9
	v_add_f32_e32 v12, v12, v13
	v_add_f32_e32 v13, v14, v15
	v_add_f32_e32 v12, v12, v13
	v_add_f32_e32 v8, v8, v12
	v_add_f32_e32 v16, v16, v17
	v_add_f32_e32 v17, v18, v19
	v_add_f32_e32 v16, v16, v17
	v_add_f32_e32 v20, v20, v21
	v_add_f32_e32 v21, v22, v23
	v_add_f32_e32 v20, v20, v21
	v_add_f32_e32 v16, v16, v20
	global_store_dword v[4:5], v8, off
	global_store_dword v[24:25], v16, off
	s_branch .LBB0_1289
.LBB0_1300:
	s_and_saveexec_b64 s[56:57], s[0:1]
	s_cbranch_execz .LBB0_1285
	v_lshlrev_b32_e32 v2, 1, v91
	v_lshlrev_b32_e32 v7, 1, v92
	v_add_u32_e32 v2, 0xfffe7ff0, v2
	v_add_u32_e32 v7, 0xfffe7ff0, v7
	ds_read_b128 v[8:11], v2
	ds_read_b128 v[12:15], v2 offset:16
	ds_read_b128 v[16:19], v7
	ds_read_b128 v[20:23], v7 offset:16
	s_or_b32 s54, s54, 0x3fe0
	v_lshl_add_u64 v[2:3], s[54:55], 0, v[48:49]
	v_mad_u64_u32 v[4:5], s[58:59], v2, s63, v[66:67]
	v_mad_i32_i24 v5, v3, s63, v5
	v_lshl_add_u64 v[2:3], s[54:55], 0, v[42:43]
	v_mad_u64_u32 v[24:25], s[58:59], v2, s63, v[66:67]
	v_mad_i32_i24 v25, v3, s63, v25
	s_waitcnt lgkmcnt(0)
	v_add_f32_e32 v8, v8, v9
	v_add_f32_e32 v9, v10, v11
	v_add_f32_e32 v8, v8, v9
	v_add_f32_e32 v12, v12, v13
	v_add_f32_e32 v13, v14, v15
	v_add_f32_e32 v12, v12, v13
	v_add_f32_e32 v8, v8, v12
	v_add_f32_e32 v16, v16, v17
	v_add_f32_e32 v17, v18, v19
	v_add_f32_e32 v16, v16, v17
	v_add_f32_e32 v20, v20, v21
	v_add_f32_e32 v21, v22, v23
	v_add_f32_e32 v20, v20, v21
	v_add_f32_e32 v16, v16, v20
	global_store_dword v[4:5], v8, off
	global_store_dword v[24:25], v16, off
	s_branch .LBB0_1285
